# P0: all big transposes per-wave (6 matrices), adaLN item loads issued up front (silu staging + K loop), S5 item loads batched
# speedup vs baseline: 1.0076x; 1.0008x over previous
; DI void phase0(const Params& p, unsigned char* smem, const int tid, const int vb, const int nvb) {
;     ...
;             const int g = it - NTR - NADA;
;             const float dtf = expf(p.in[14][g]);
;             const double dt = (double)dtf;
;             float2* apow = (float2*)(ws + OFF_APOW);
;             for (int idx = tid; idx < 64 * 65; idx += 256) {
;                 int pp = idx / 65, tau = idx % 65;
;                 double lr = p.in[12][g * 64 + pp], li = p.in[13][g * 64 + pp];
;                 double rev = li * dt * (double)tau * 0.15915494309189535;
;                 rev -= rint(rev);
;                 float mag = expf((float)(lr * dt * (double)tau));
;                 apow[((size_t)g * 65 + tau) * 64 + pp] = make_float2(mag * __builtin_amdgcn_cosf((float)rev), mag * __builtin_amdgcn_sinf((float)rev));
;             }
;             if (tid < 64) {
;                 int pp = tid;
;                 float lr = p.in[12][g * 64 + pp], li = p.in[13][g * 64 + pp];
;                 float em1 = expm1f(lr * dtf), mag = em1 + 1.f;
;                 double rev = (double)li * dt * 0.15915494309189535;
;                 double revh = 0.5 * rev;
;                 rev -= rint(rev); revh -= rint(revh);
;                 float sh = __builtin_amdgcn_sinf((float)revh);
;                 float arm1 = em1 - 2.f * mag * sh * sh;
;                 float ai = mag * __builtin_amdgcn_sinf((float)rev);
;                 float den = lr * lr + li * li;
;                 float zr = (arm1 * lr + ai * li) / den, zi = (ai * lr - arm1 * li) / den;
;                 float2* bb = (float2*)(ws + OFF_BBAR);
;                 for (int c2 = 0; c2 < 16; ++c2) {
;                     float br = p.in[15][(size_t)(g * 64 + pp) * 16 + c2], bi = p.in[16][(size_t)(g * 64 + pp) * 16 + c2];
.LBB0_22:
	s_movk_i32 s4, 0x1a0
	v_cmp_gt_i32_e32 vcc, s4, v67
	s_movk_i32 s4, 0x100f
	s_nop 0
	v_cndmask_b32_e32 v0, v122, v123, vcc
	v_add_u32_e32 v4, v0, v67
	v_cmp_lt_i32_e32 vcc, s4, v4
	s_and_saveexec_b64 s[4:5], vcc
	s_xor_b64 s[22:23], exec, s[4:5]
	s_cbranch_execz .LBB0_38
	s_movk_i32 s4, 0x118f
	v_cmp_lt_u32_e32 vcc, s4, v4
	s_and_saveexec_b64 s[4:5], vcc
	s_xor_b64 s[24:25], exec, s[4:5]
	s_cbranch_execz .LBB0_29
	v_add_u32_e32 v68, 0xffffee70, v4
	v_lshl_add_u64 v[0:1], v[68:69], 2, s[84:85]
	global_load_dword v3, v[0:1], off
	s_movk_i32 s18, 0x41
	s_mov_b64 s[4:5], 0
	s_waitcnt vmcnt(0)
	v_mul_f32_e32 v0, 0x3fb8aa3b, v3
	v_fma_f32 v1, v3, s38, -v0
	v_rndne_f32_e32 v2, v0
	v_fmac_f32_e32 v1, 0x32a5705f, v3
	v_sub_f32_e32 v0, v0, v2
	v_add_f32_e32 v0, v0, v1
	v_cvt_i32_f32_e32 v4, v2
	v_exp_f32_e32 v5, v0
	v_cmp_ngt_f32_e32 vcc, s39, v3
	v_lshlrev_b32_e32 v2, 6, v68
	v_mad_u64_u32 v[0:1], s[26:27], v68, s18, 0
	v_ldexp_f32 v4, v5, v4
	v_cndmask_b32_e32 v4, 0, v4, vcc
	v_cmp_nlt_f32_e32 vcc, s40, v3
	v_mov_b32_e32 v3, v71
	s_nop 0
	v_cndmask_b32_e32 v9, v124, v4, vcc
	v_cvt_f64_f32_e32 v[14:15], v9
	v_and_b32_e32 v198, 0xffff, v3
	v_mul_u32_u24_e32 v198, 0xfc1, v198
	v_lshrrev_b32_e32 v198, 18, v198
	v_min_u32_e32 v198, 63, v198
	v_add_u32_e32 v198, v2, v198
	v_mov_b32_e32 v199, 0
	v_lshlrev_b64 v[202:203], 2, v[198:199]
	v_lshl_add_u64 v[204:205], s[82:83], 0, v[202:203]
	v_lshl_add_u64 v[202:203], s[80:81], 0, v[202:203]
	global_load_dword v196, v[202:203], off
	global_load_dword v197, v[204:205], off
	s_waitcnt vmcnt(0)
.LBB0_25:
	s_movk_i32 s18, 0xfc1
	v_mul_u32_u24_sdwa v4, v3, s18 dst_sel:DWORD dst_unused:UNUSED_PAD src0_sel:WORD_0 src1_sel:DWORD
	v_lshrrev_b32_e32 v8, 18, v4
	v_add_u32_e32 v68, v2, v8
	v_lshlrev_b64 v[4:5], 2, v[68:69]
	v_lshl_add_u64 v[6:7], s[80:81], 0, v[4:5]
	v_lshl_add_u64 v[4:5], s[82:83], 0, v[4:5]
	v_mul_lo_u16_e32 v5, 0x41, v8
	v_add_u32_e32 v4, 0x100, v3
	s_movk_i32 s18, 0xf3f
	v_sub_u16_e32 v68, v3, v5
	v_cmp_lt_u32_e32 vcc, s18, v3
	v_mov_b32_e32 v3, v4
	v_cvt_f64_u32_e32 v[4:5], v68
	v_lshl_add_u64 v[6:7], v[0:1], 0, v[68:69]
	v_lshlrev_b32_e32 v68, 3, v8
	s_or_b64 s[4:5], vcc, s[4:5]
	v_lshlrev_b64 v[6:7], 9, v[6:7]
	v_lshl_add_u64 v[6:7], s[8:9], 0, v[6:7]
	v_lshl_add_u64 v[6:7], v[6:7], 0, v[68:69]
	s_waitcnt vmcnt(2)
	v_cvt_f64_f32_e32 v[10:11], v196
	s_waitcnt vmcnt(1)
	v_cvt_f64_f32_e32 v[12:13], v197
	v_and_b32_e32 v198, 0xffff, v3
	v_mul_u32_u24_e32 v198, 0xfc1, v198
	v_lshrrev_b32_e32 v198, 18, v198
	v_min_u32_e32 v198, 63, v198
	v_add_u32_e32 v198, v2, v198
	v_mov_b32_e32 v199, 0
	v_lshlrev_b64 v[202:203], 2, v[198:199]
	v_lshl_add_u64 v[204:205], s[82:83], 0, v[202:203]
	v_lshl_add_u64 v[202:203], s[80:81], 0, v[202:203]
	global_load_dword v196, v[202:203], off
	global_load_dword v197, v[204:205], off
	v_mul_f64 v[12:13], v[14:15], v[12:13]
	v_mul_f64 v[10:11], v[14:15], v[10:11]
	v_mul_f64 v[12:13], v[12:13], v[4:5]
	v_mul_f64 v[4:5], v[10:11], v[4:5]
	v_mul_f64 v[10:11], v[12:13], s[16:17]
	v_cvt_f32_f64_e32 v8, v[4:5]
	v_rndne_f64_e32 v[4:5], v[10:11]
	v_mul_f32_e32 v10, 0x3fb8aa3b, v8
	v_fma_f64 v[4:5], v[12:13], s[16:17], -v[4:5]
	v_fma_f32 v11, v8, s38, -v10
	v_rndne_f32_e32 v12, v10
	v_fmac_f32_e32 v11, 0x32a5705f, v8
	v_sub_f32_e32 v10, v10, v12
	v_add_f32_e32 v10, v10, v11
	v_cvt_i32_f32_e32 v12, v12
	v_exp_f32_e32 v10, v10
	v_cvt_f32_f64_e32 v5, v[4:5]
	v_cos_f32_e32 v4, v5
	v_sin_f32_e32 v5, v5
	v_ldexp_f32 v10, v10, v12
	v_cmp_ngt_f32_e32 vcc, s39, v8
	s_nop 1
	v_cndmask_b32_e32 v10, 0, v10, vcc
	v_cmp_nlt_f32_e32 vcc, s40, v8
	s_nop 1
	v_cndmask_b32_e32 v8, v124, v10, vcc
	v_pk_mul_f32 v[4:5], v[8:9], v[4:5] op_sel_hi:[0,1]
	global_store_dwordx2 v[6:7], v[4:5], off
	s_andn2_b64 exec, exec, s[4:5]
	s_cbranch_execnz .LBB0_25
	s_or_b64 exec, exec, s[4:5]
	s_and_saveexec_b64 s[26:27], s[0:1]
	s_cbranch_execz .LBB0_28
	v_or_b32_e32 v68, v2, v71
	v_lshlrev_b64 v[0:1], 2, v[68:69]
	v_lshl_add_u64 v[2:3], s[80:81], 0, v[0:1]
	global_load_dword v12, v[2:3], off
	v_lshl_add_u64 v[0:1], s[82:83], 0, v[0:1]
	global_load_dword v13, v[0:1], off
	v_lshlrev_b64 v[2:3], 6, v[68:69]
	v_lshl_add_u64 v[0:1], s[86:87], 0, v[2:3]
	v_readlane_b32 s72, v254, 20
	v_readlane_b32 s73, v254, 21
	s_mov_b32 s4, 0x43000000
	v_lshlrev_b64 v[4:5], 7, v[68:69]
	v_lshl_add_u64 v[2:3], s[72:73], 0, v[2:3]
	global_load_dword v10, v[2:3], off
	global_load_dword v8, v[0:1], off
	global_load_dwordx4 v[164:167], v[2:3], off
	global_load_dwordx4 v[168:171], v[2:3], off offset:16
	global_load_dwordx4 v[172:175], v[2:3], off offset:32
	global_load_dwordx4 v[176:179], v[2:3], off offset:48
	global_load_dwordx4 v[180:183], v[0:1], off
	global_load_dwordx4 v[184:187], v[0:1], off offset:16
	global_load_dwordx4 v[188:191], v[0:1], off offset:32
	global_load_dwordx4 v[192:195], v[0:1], off offset:48
	v_lshl_add_u64 v[6:7], s[10:11], 0, v[4:5]
	v_readlane_b32 s74, v254, 22
	v_readlane_b32 s75, v254, 23
	v_readlane_b32 s76, v254, 24
	v_readlane_b32 s77, v254, 25
	v_readlane_b32 s78, v254, 26
	v_readlane_b32 s79, v254, 27
	v_readlane_b32 s80, v254, 28
	v_readlane_b32 s81, v254, 29
	v_readlane_b32 s82, v254, 30
	v_readlane_b32 s83, v254, 31
	v_readlane_b32 s84, v254, 32
	v_readlane_b32 s85, v254, 33
	v_readlane_b32 s86, v254, 34
	v_readlane_b32 s87, v254, 35
	v_readlane_b32 s72, v254, 36
	v_readlane_b32 s73, v254, 37
	v_readlane_b32 s74, v254, 38
	v_readlane_b32 s75, v254, 39
	v_readlane_b32 s80, v254, 44
	v_readlane_b32 s81, v254, 45
	v_readlane_b32 s82, v254, 46
	v_readlane_b32 s83, v254, 47
	v_readlane_b32 s84, v254, 48
	v_readlane_b32 s85, v254, 49
	v_readlane_b32 s86, v254, 50
	v_readlane_b32 s87, v254, 51
	v_readlane_b32 s76, v254, 40
	v_readlane_b32 s77, v254, 41
	v_readlane_b32 s78, v254, 42
	v_readlane_b32 s79, v254, 43
	s_waitcnt vmcnt(11)
; DI void phase0(const Params& p, unsigned char* smem, const int tid, const int vb, const int nvb) {
;     ...
;                 int pp = tid;
;                 float lr = p.in[12][g * 64 + pp], li = p.in[13][g * 64 + pp];
;                 float em1 = expm1f(lr * dtf), mag = em1 + 1.f;
;                 double rev = (double)li * dt * 0.15915494309189535;
;                 double revh = 0.5 * rev;
;                 rev -= rint(rev); revh -= rint(revh);
;                 float sh = __builtin_amdgcn_sinf((float)revh);
;                 float arm1 = em1 - 2.f * mag * sh * sh;
;                 float ai = mag * __builtin_amdgcn_sinf((float)rev);
;                 float den = lr * lr + li * li;
;                 float zr = (arm1 * lr + ai * li) / den, zi = (ai * lr - arm1 * li) / den;
;                 float2* bb = (float2*)(ws + OFF_BBAR);
;                 for (int c2 = 0; c2 < 16; ++c2) {
;                     float br = p.in[15][(size_t)(g * 64 + pp) * 16 + c2], bi = p.in[16][(size_t)(g * 64 + pp) * 16 + c2];
;                     bb[(size_t)(g * 64 + pp) * 16 + c2] = make_float2(zr * br - zi * bi, zr * bi + zi * br);
	v_mul_f32_e32 v9, v9, v12
	v_mul_f32_e32 v11, 0x3fb8aa3b, v9
	s_waitcnt vmcnt(10)
	v_cvt_f64_f32_e32 v[16:17], v13
	v_pk_mul_f32 v[18:19], v[12:13], v[12:13]
	v_mul_f64 v[16:17], v[14:15], v[16:17]
	v_rndne_f32_e32 v11, v11
	v_mov_b32_e32 v20, v13
	v_pk_add_f32 v[14:15], v[18:19], v[18:19] op_sel:[0,1] op_sel_hi:[0,1]
	v_mul_f64 v[18:19], v[16:17], s[16:17]
	v_fmamk_f32 v13, v11, 0xbf317218, v9
	v_rndne_f64_e32 v[24:25], v[18:19]
	v_fmac_f32_e32 v13, 0x3102e308, v11
	v_cvt_i32_f32_e32 v21, v11
	v_fma_f64 v[16:17], v[16:17], s[16:17], -v[24:25]
	v_fmamk_f32 v24, v13, 0x395133b1, v121
	v_mul_f64 v[22:23], v[18:19], 0.5
	v_cvt_f32_f64_e32 v16, v[16:17]
	v_fmaak_f32 v17, v13, v24, 0x3c0887f9
	v_rndne_f64_e32 v[22:23], v[22:23]
	v_fmaak_f32 v17, v13, v17, 0x3d2aaa81
	v_fma_f64 v[18:19], v[18:19], 0.5, -v[22:23]
	v_fmaak_f32 v17, v13, v17, 0x3e2aaaab
	v_cvt_f32_f64_e32 v18, v[18:19]
	v_ldexp_f32 v19, 1.0, v21
	v_cmp_eq_f32_e32 vcc, s4, v11
	v_fma_f32 v17, v13, v17, 0.5
	v_mul_f32_e32 v17, v13, v17
	v_cndmask_b32_e32 v11, v19, v125, vcc
	v_add_f32_e32 v19, -1.0, v11
	v_fmac_f32_e32 v13, v13, v17
	v_fmac_f32_e32 v19, v11, v13
	v_add_f32_e32 v11, v19, v19
	s_mov_b32 s4, 0x42b17217
	v_cndmask_b32_e32 v11, v19, v11, vcc
	v_cmp_nlt_f32_e32 vcc, s4, v9
	s_mov_b32 s4, 0xc1880000
	v_sin_f32_e32 v16, v16
	v_sin_f32_e32 v18, v18
	v_cndmask_b32_e32 v11, v124, v11, vcc
	v_cmp_ngt_f32_e32 vcc, s4, v9
	s_nop 1
	v_cndmask_b32_e32 v9, -1.0, v11, vcc
	v_add_f32_e32 v11, 1.0, v9
	v_add_f32_e32 v13, v11, v11
	v_mul_f32_e32 v17, v16, v11
	v_mul_f32_e32 v11, v18, v13
	v_fma_f32 v16, -v18, v11, v9
	v_pk_mul_f32 v[18:19], v[20:21], v[16:17] op_sel:[0,1] op_sel_hi:[0,0]
	v_pk_fma_f32 v[20:21], v[12:13], v[16:17], v[18:19]
	v_pk_fma_f32 v[12:13], v[12:13], v[16:17], v[18:19] op_sel_hi:[0,1,1] neg_lo:[0,0,1] neg_hi:[0,0,1]
	v_div_scale_f32 v9, s[4:5], v15, v15, v13
	v_div_scale_f32 v12, s[4:5], v14, v14, v20
	v_rcp_f32_e32 v16, v9
	v_rcp_f32_e32 v17, v12
	v_div_scale_f32 v11, vcc, v13, v15, v13
	v_fma_f32 v19, -v9, v16, 1.0
	v_fma_f32 v21, -v12, v17, 1.0
	v_fmac_f32_e32 v16, v19, v16
	v_div_scale_f32 v18, s[4:5], v20, v14, v20
	v_fmac_f32_e32 v17, v21, v17
	v_mul_f32_e32 v19, v11, v16
	v_mul_f32_e32 v21, v18, v17
	v_fma_f32 v22, -v9, v19, v11
	v_fma_f32 v23, -v12, v21, v18
	v_fmac_f32_e32 v19, v22, v16
	v_fmac_f32_e32 v21, v23, v17
	v_fma_f32 v9, -v9, v19, v11
	v_fma_f32 v11, -v12, v21, v18
	v_div_fmas_f32 v9, v9, v16, v19
	s_mov_b64 vcc, s[4:5]
	v_div_fixup_f32 v13, v9, v15, v13
	v_div_fmas_f32 v9, v11, v17, v21
	v_div_fixup_f32 v12, v9, v14, v20
	s_waitcnt vmcnt(9)
	v_pk_mul_f32 v[10:11], v[10:11], v[12:13] op_sel:[0,1] op_sel_hi:[0,0]
	s_waitcnt vmcnt(8)
	v_pk_fma_f32 v[14:15], v[8:9], v[12:13], v[10:11] neg_lo:[0,0,1] neg_hi:[0,0,1]
	v_pk_fma_f32 v[8:9], v[8:9], v[12:13], v[10:11] op_sel_hi:[0,1,1]
	v_mov_b32_e32 v15, v9
	global_store_dwordx2 v[6:7], v[14:15], off
	s_waitcnt vmcnt(1)
; DI void phase0(const Params& p, unsigned char* smem, const int tid, const int vb, const int nvb) {
;     ...
;                 for (int c2 = 0; c2 < 16; ++c2) {
;                     float br = p.in[15][(size_t)(g * 64 + pp) * 16 + c2], bi = p.in[16][(size_t)(g * 64 + pp) * 16 + c2];
;                     bb[(size_t)(g * 64 + pp) * 16 + c2] = make_float2(zr * br - zi * bi, zr * bi + zi * br);
;                 }
	v_mov_b32_e32 v6, v165
	s_nop 0
	v_mov_b32_e32 v8, v181
	v_or_b32_e32 v10, 8, v4
	v_mov_b32_e32 v11, v5
	v_lshl_add_u64 v[10:11], s[10:11], 0, v[10:11]
	v_pk_mul_f32 v[6:7], v[6:7], v[12:13] op_sel:[0,1] op_sel_hi:[0,0]
	v_pk_fma_f32 v[14:15], v[8:9], v[12:13], v[6:7] neg_lo:[0,0,1] neg_hi:[0,0,1]
	v_pk_fma_f32 v[6:7], v[8:9], v[12:13], v[6:7] op_sel_hi:[0,1,1]
	v_mov_b32_e32 v15, v7
	global_store_dwordx2 v[10:11], v[14:15], off
	v_mov_b32_e32 v6, v166
	v_mov_b32_e32 v8, v182
	v_or_b32_e32 v10, 16, v4
	v_mov_b32_e32 v11, v5
	v_lshl_add_u64 v[10:11], s[10:11], 0, v[10:11]
	v_pk_mul_f32 v[6:7], v[6:7], v[12:13] op_sel:[0,1] op_sel_hi:[0,0]
	v_pk_fma_f32 v[14:15], v[8:9], v[12:13], v[6:7] neg_lo:[0,0,1] neg_hi:[0,0,1]
	v_pk_fma_f32 v[6:7], v[8:9], v[12:13], v[6:7] op_sel_hi:[0,1,1]
	v_mov_b32_e32 v15, v7
	global_store_dwordx2 v[10:11], v[14:15], off
	v_mov_b32_e32 v6, v167
	v_mov_b32_e32 v8, v183
	v_or_b32_e32 v10, 24, v4
	v_mov_b32_e32 v11, v5
	v_lshl_add_u64 v[10:11], s[10:11], 0, v[10:11]
	v_pk_mul_f32 v[6:7], v[6:7], v[12:13] op_sel:[0,1] op_sel_hi:[0,0]
	v_pk_fma_f32 v[14:15], v[8:9], v[12:13], v[6:7] neg_lo:[0,0,1] neg_hi:[0,0,1]
	v_pk_fma_f32 v[6:7], v[8:9], v[12:13], v[6:7] op_sel_hi:[0,1,1]
	v_mov_b32_e32 v15, v7
	global_store_dwordx2 v[10:11], v[14:15], off
	v_mov_b32_e32 v6, v168
	v_mov_b32_e32 v8, v184
	v_or_b32_e32 v10, 32, v4
	v_mov_b32_e32 v11, v5
	v_lshl_add_u64 v[10:11], s[10:11], 0, v[10:11]
	v_pk_mul_f32 v[6:7], v[6:7], v[12:13] op_sel:[0,1] op_sel_hi:[0,0]
	v_pk_fma_f32 v[14:15], v[8:9], v[12:13], v[6:7] neg_lo:[0,0,1] neg_hi:[0,0,1]
	v_pk_fma_f32 v[6:7], v[8:9], v[12:13], v[6:7] op_sel_hi:[0,1,1]
	v_mov_b32_e32 v15, v7
	global_store_dwordx2 v[10:11], v[14:15], off
	v_mov_b32_e32 v6, v169
	v_mov_b32_e32 v8, v185
	v_or_b32_e32 v10, 40, v4
	v_mov_b32_e32 v11, v5
	v_lshl_add_u64 v[10:11], s[10:11], 0, v[10:11]
	v_pk_mul_f32 v[6:7], v[6:7], v[12:13] op_sel:[0,1] op_sel_hi:[0,0]
	v_pk_fma_f32 v[14:15], v[8:9], v[12:13], v[6:7] neg_lo:[0,0,1] neg_hi:[0,0,1]
	v_pk_fma_f32 v[6:7], v[8:9], v[12:13], v[6:7] op_sel_hi:[0,1,1]
	v_mov_b32_e32 v15, v7
	global_store_dwordx2 v[10:11], v[14:15], off
	v_mov_b32_e32 v6, v170
	v_mov_b32_e32 v8, v186
	v_or_b32_e32 v10, 48, v4
	v_mov_b32_e32 v11, v5
	v_lshl_add_u64 v[10:11], s[10:11], 0, v[10:11]
	v_pk_mul_f32 v[6:7], v[12:13], v[6:7] op_sel:[1,0] op_sel_hi:[0,0]
	v_pk_fma_f32 v[14:15], v[12:13], v[8:9], v[6:7] neg_lo:[0,0,1] neg_hi:[0,0,1]
	v_pk_fma_f32 v[6:7], v[12:13], v[8:9], v[6:7] op_sel_hi:[1,0,1]
	s_nop 0
	v_mov_b32_e32 v15, v7
	global_store_dwordx2 v[10:11], v[14:15], off
	v_mov_b32_e32 v6, v171
	v_mov_b32_e32 v8, v187
	v_or_b32_e32 v10, 56, v4
	v_mov_b32_e32 v11, v5
	v_lshl_add_u64 v[10:11], s[10:11], 0, v[10:11]
	v_pk_mul_f32 v[6:7], v[12:13], v[6:7] op_sel:[1,0] op_sel_hi:[0,0]
	v_pk_fma_f32 v[14:15], v[12:13], v[8:9], v[6:7] neg_lo:[0,0,1] neg_hi:[0,0,1]
	v_pk_fma_f32 v[6:7], v[12:13], v[8:9], v[6:7] op_sel_hi:[1,0,1]
	s_nop 0
	v_mov_b32_e32 v15, v7
	global_store_dwordx2 v[10:11], v[14:15], off
	v_mov_b32_e32 v6, v172
	v_mov_b32_e32 v8, v188
	v_or_b32_e32 v10, 64, v4
	v_mov_b32_e32 v11, v5
	v_lshl_add_u64 v[10:11], s[10:11], 0, v[10:11]
	v_pk_mul_f32 v[6:7], v[12:13], v[6:7] op_sel:[1,0] op_sel_hi:[0,0]
	v_pk_fma_f32 v[14:15], v[12:13], v[8:9], v[6:7] neg_lo:[0,0,1] neg_hi:[0,0,1]
	v_pk_fma_f32 v[6:7], v[12:13], v[8:9], v[6:7] op_sel_hi:[1,0,1]
	s_nop 0
	v_mov_b32_e32 v15, v7
	global_store_dwordx2 v[10:11], v[14:15], off
	v_mov_b32_e32 v6, v173
	v_mov_b32_e32 v8, v189
	v_or_b32_e32 v10, 0x48, v4
	v_mov_b32_e32 v11, v5
	v_lshl_add_u64 v[10:11], s[10:11], 0, v[10:11]
	v_pk_mul_f32 v[6:7], v[12:13], v[6:7] op_sel:[1,0] op_sel_hi:[0,0]
	v_pk_fma_f32 v[14:15], v[12:13], v[8:9], v[6:7] neg_lo:[0,0,1] neg_hi:[0,0,1]
	v_pk_fma_f32 v[6:7], v[12:13], v[8:9], v[6:7] op_sel_hi:[1,0,1]
	s_nop 0
	v_mov_b32_e32 v15, v7
	global_store_dwordx2 v[10:11], v[14:15], off
	v_mov_b32_e32 v6, v174
	v_mov_b32_e32 v8, v190
	v_or_b32_e32 v10, 0x50, v4
	v_mov_b32_e32 v11, v5
	v_lshl_add_u64 v[10:11], s[10:11], 0, v[10:11]
	v_pk_mul_f32 v[6:7], v[12:13], v[6:7] op_sel:[1,0] op_sel_hi:[0,0]
	v_pk_fma_f32 v[14:15], v[12:13], v[8:9], v[6:7] neg_lo:[0,0,1] neg_hi:[0,0,1]
	v_pk_fma_f32 v[6:7], v[12:13], v[8:9], v[6:7] op_sel_hi:[1,0,1]
	s_nop 0
	v_mov_b32_e32 v15, v7
	global_store_dwordx2 v[10:11], v[14:15], off
	v_mov_b32_e32 v6, v175
	v_mov_b32_e32 v8, v191
	v_or_b32_e32 v10, 0x58, v4
	v_mov_b32_e32 v11, v5
	v_lshl_add_u64 v[10:11], s[10:11], 0, v[10:11]
	v_pk_mul_f32 v[6:7], v[12:13], v[6:7] op_sel:[1,0] op_sel_hi:[0,0]
	v_pk_fma_f32 v[14:15], v[12:13], v[8:9], v[6:7] neg_lo:[0,0,1] neg_hi:[0,0,1]
	v_pk_fma_f32 v[6:7], v[12:13], v[8:9], v[6:7] op_sel_hi:[1,0,1]
	s_nop 0
	v_mov_b32_e32 v15, v7
	global_store_dwordx2 v[10:11], v[14:15], off
	v_mov_b32_e32 v6, v176
	v_mov_b32_e32 v8, v192
	v_or_b32_e32 v10, 0x60, v4
	v_mov_b32_e32 v11, v5
	v_lshl_add_u64 v[10:11], s[10:11], 0, v[10:11]
	v_pk_mul_f32 v[6:7], v[12:13], v[6:7] op_sel:[1,0] op_sel_hi:[0,0]
	v_pk_fma_f32 v[14:15], v[12:13], v[8:9], v[6:7] neg_lo:[0,0,1] neg_hi:[0,0,1]
	v_pk_fma_f32 v[6:7], v[12:13], v[8:9], v[6:7] op_sel_hi:[1,0,1]
	s_nop 0
	v_mov_b32_e32 v15, v7
	global_store_dwordx2 v[10:11], v[14:15], off
	v_mov_b32_e32 v6, v177
	v_mov_b32_e32 v8, v193
	v_or_b32_e32 v10, 0x68, v4
	v_mov_b32_e32 v11, v5
	v_lshl_add_u64 v[10:11], s[10:11], 0, v[10:11]
	v_pk_mul_f32 v[6:7], v[12:13], v[6:7] op_sel:[1,0] op_sel_hi:[0,0]
	v_pk_fma_f32 v[14:15], v[12:13], v[8:9], v[6:7] neg_lo:[0,0,1] neg_hi:[0,0,1]
	v_pk_fma_f32 v[6:7], v[12:13], v[8:9], v[6:7] op_sel_hi:[1,0,1]
	s_nop 0
	v_mov_b32_e32 v15, v7
	global_store_dwordx2 v[10:11], v[14:15], off
	v_mov_b32_e32 v6, v178
	v_mov_b32_e32 v8, v194
	v_or_b32_e32 v10, 0x70, v4
	v_mov_b32_e32 v11, v5
	v_lshl_add_u64 v[10:11], s[10:11], 0, v[10:11]
	v_or_b32_e32 v4, 0x78, v4
	v_lshl_add_u64 v[4:5], s[10:11], 0, v[4:5]
	v_pk_mul_f32 v[6:7], v[12:13], v[6:7] op_sel:[1,0] op_sel_hi:[0,0]
	v_pk_fma_f32 v[14:15], v[12:13], v[8:9], v[6:7] neg_lo:[0,0,1] neg_hi:[0,0,1]
	v_pk_fma_f32 v[6:7], v[12:13], v[8:9], v[6:7] op_sel_hi:[1,0,1]
	s_nop 0
	v_mov_b32_e32 v15, v7
	global_store_dwordx2 v[10:11], v[14:15], off
	v_mov_b32_e32 v2, v179
	s_nop 0
	v_mov_b32_e32 v0, v195
	v_pk_mul_f32 v[2:3], v[12:13], v[2:3] op_sel:[1,0] op_sel_hi:[0,0]
	v_pk_fma_f32 v[6:7], v[12:13], v[0:1], v[2:3] neg_lo:[0,0,1] neg_hi:[0,0,1]
	v_pk_fma_f32 v[0:1], v[12:13], v[0:1], v[2:3] op_sel_hi:[1,0,1]
	s_nop 0
	v_mov_b32_e32 v7, v1
	global_store_dwordx2 v[4:5], v[6:7], off

; DI void phase0(const Params& p, unsigned char* smem, const int tid, const int vb, const int nvb) {
;     ...
;             for (int i = tid; i < 4096; i += 256) { float v = p.in[1][i]; sc[i] = v / (1.f + __expf(-v)); }
.LBB0_31:
	s_mov_b64 s[26:27], 0x400
	global_load_dword v200, v[0:1], off
	v_lshl_add_u64 v[0:1], v[0:1], 0, s[26:27]
	global_load_dword v201, v[0:1], off
	v_lshl_add_u64 v[0:1], v[0:1], 0, s[26:27]
	global_load_dword v202, v[0:1], off
	v_lshl_add_u64 v[0:1], v[0:1], 0, s[26:27]
	global_load_dword v203, v[0:1], off
	v_lshl_add_u64 v[0:1], v[0:1], 0, s[26:27]
	global_load_dword v204, v[0:1], off
	v_lshl_add_u64 v[0:1], v[0:1], 0, s[26:27]
	global_load_dword v205, v[0:1], off
	v_lshl_add_u64 v[0:1], v[0:1], 0, s[26:27]
	global_load_dword v206, v[0:1], off
	v_lshl_add_u64 v[0:1], v[0:1], 0, s[26:27]
	global_load_dword v207, v[0:1], off
	v_lshl_add_u64 v[0:1], v[0:1], 0, s[26:27]
	global_load_dword v208, v[0:1], off
	v_lshl_add_u64 v[0:1], v[0:1], 0, s[26:27]
	global_load_dword v209, v[0:1], off
	v_lshl_add_u64 v[0:1], v[0:1], 0, s[26:27]
	global_load_dword v210, v[0:1], off
	v_lshl_add_u64 v[0:1], v[0:1], 0, s[26:27]
	global_load_dword v211, v[0:1], off
	v_lshl_add_u64 v[0:1], v[0:1], 0, s[26:27]
	global_load_dword v212, v[0:1], off
	v_lshl_add_u64 v[0:1], v[0:1], 0, s[26:27]
	global_load_dword v213, v[0:1], off
	v_lshl_add_u64 v[0:1], v[0:1], 0, s[26:27]
	global_load_dword v214, v[0:1], off
	v_lshl_add_u64 v[0:1], v[0:1], 0, s[26:27]
	global_load_dword v215, v[0:1], off
	s_waitcnt vmcnt(15)
	v_mov_b32_e32 v5, v200
	v_mul_f32_e32 v6, 0xbfb8aa3b, v5
	v_exp_f32_e32 v6, v6
	s_nop 0
	v_add_f32_e32 v6, 1.0, v6
	v_div_scale_f32 v7, s[26:27], v6, v6, v5
	v_rcp_f32_e32 v8, v7
	v_div_scale_f32 v9, vcc, v5, v6, v5
	v_fma_f32 v10, -v7, v8, 1.0
	v_fmac_f32_e32 v8, v10, v8
	v_mul_f32_e32 v10, v9, v8
	v_fma_f32 v11, -v7, v10, v9
	v_fmac_f32_e32 v10, v11, v8
	v_fma_f32 v7, -v7, v10, v9
	v_div_fmas_f32 v7, v7, v8, v10
	v_div_fixup_f32 v5, v7, v6, v5
	ds_write_b32 v3, v5
	v_add_u32_e32 v3, 0x400, v3
	s_waitcnt vmcnt(14)
	v_mov_b32_e32 v5, v201
	v_mul_f32_e32 v6, 0xbfb8aa3b, v5
	v_exp_f32_e32 v6, v6
	s_nop 0
	v_add_f32_e32 v6, 1.0, v6
	v_div_scale_f32 v7, s[26:27], v6, v6, v5
	v_rcp_f32_e32 v8, v7
	v_div_scale_f32 v9, vcc, v5, v6, v5
	v_fma_f32 v10, -v7, v8, 1.0
	v_fmac_f32_e32 v8, v10, v8
	v_mul_f32_e32 v10, v9, v8
	v_fma_f32 v11, -v7, v10, v9
	v_fmac_f32_e32 v10, v11, v8
	v_fma_f32 v7, -v7, v10, v9
	v_div_fmas_f32 v7, v7, v8, v10
	v_div_fixup_f32 v5, v7, v6, v5
	ds_write_b32 v3, v5
	v_add_u32_e32 v3, 0x400, v3
	s_waitcnt vmcnt(13)
	v_mov_b32_e32 v5, v202
	v_mul_f32_e32 v6, 0xbfb8aa3b, v5
	v_exp_f32_e32 v6, v6
	s_nop 0
	v_add_f32_e32 v6, 1.0, v6
	v_div_scale_f32 v7, s[26:27], v6, v6, v5
	v_rcp_f32_e32 v8, v7
	v_div_scale_f32 v9, vcc, v5, v6, v5
	v_fma_f32 v10, -v7, v8, 1.0
	v_fmac_f32_e32 v8, v10, v8
	v_mul_f32_e32 v10, v9, v8
	v_fma_f32 v11, -v7, v10, v9
	v_fmac_f32_e32 v10, v11, v8
	v_fma_f32 v7, -v7, v10, v9
	v_div_fmas_f32 v7, v7, v8, v10
	v_div_fixup_f32 v5, v7, v6, v5
	ds_write_b32 v3, v5
	v_add_u32_e32 v3, 0x400, v3
	s_waitcnt vmcnt(12)
	v_mov_b32_e32 v5, v203
	v_mul_f32_e32 v6, 0xbfb8aa3b, v5
	v_exp_f32_e32 v6, v6
	s_nop 0
	v_add_f32_e32 v6, 1.0, v6
	v_div_scale_f32 v7, s[26:27], v6, v6, v5
	v_rcp_f32_e32 v8, v7
	v_div_scale_f32 v9, vcc, v5, v6, v5
	v_fma_f32 v10, -v7, v8, 1.0
	v_fmac_f32_e32 v8, v10, v8
	v_mul_f32_e32 v10, v9, v8
	v_fma_f32 v11, -v7, v10, v9
	v_fmac_f32_e32 v10, v11, v8
	v_fma_f32 v7, -v7, v10, v9
	v_div_fmas_f32 v7, v7, v8, v10
	v_div_fixup_f32 v5, v7, v6, v5
	ds_write_b32 v3, v5
	v_add_u32_e32 v3, 0x400, v3
	s_waitcnt vmcnt(11)
	v_mov_b32_e32 v5, v204
	v_mul_f32_e32 v6, 0xbfb8aa3b, v5
	v_exp_f32_e32 v6, v6
	s_nop 0
	v_add_f32_e32 v6, 1.0, v6
	v_div_scale_f32 v7, s[26:27], v6, v6, v5
	v_rcp_f32_e32 v8, v7
	v_div_scale_f32 v9, vcc, v5, v6, v5
	v_fma_f32 v10, -v7, v8, 1.0
	v_fmac_f32_e32 v8, v10, v8
	v_mul_f32_e32 v10, v9, v8
	v_fma_f32 v11, -v7, v10, v9
	v_fmac_f32_e32 v10, v11, v8
	v_fma_f32 v7, -v7, v10, v9
	v_div_fmas_f32 v7, v7, v8, v10
	v_div_fixup_f32 v5, v7, v6, v5
	ds_write_b32 v3, v5
	v_add_u32_e32 v3, 0x400, v3
	s_waitcnt vmcnt(10)
	v_mov_b32_e32 v5, v205
	v_mul_f32_e32 v6, 0xbfb8aa3b, v5
	v_exp_f32_e32 v6, v6
	s_nop 0
	v_add_f32_e32 v6, 1.0, v6
	v_div_scale_f32 v7, s[26:27], v6, v6, v5
	v_rcp_f32_e32 v8, v7
	v_div_scale_f32 v9, vcc, v5, v6, v5
	v_fma_f32 v10, -v7, v8, 1.0
	v_fmac_f32_e32 v8, v10, v8
	v_mul_f32_e32 v10, v9, v8
	v_fma_f32 v11, -v7, v10, v9
	v_fmac_f32_e32 v10, v11, v8
	v_fma_f32 v7, -v7, v10, v9
	v_div_fmas_f32 v7, v7, v8, v10
	v_div_fixup_f32 v5, v7, v6, v5
	ds_write_b32 v3, v5
	v_add_u32_e32 v3, 0x400, v3
	s_waitcnt vmcnt(9)
	v_mov_b32_e32 v5, v206
	v_mul_f32_e32 v6, 0xbfb8aa3b, v5
	v_exp_f32_e32 v6, v6
	s_nop 0
	v_add_f32_e32 v6, 1.0, v6
	v_div_scale_f32 v7, s[26:27], v6, v6, v5
	v_rcp_f32_e32 v8, v7
	v_div_scale_f32 v9, vcc, v5, v6, v5
	v_fma_f32 v10, -v7, v8, 1.0
	v_fmac_f32_e32 v8, v10, v8
	v_mul_f32_e32 v10, v9, v8
	v_fma_f32 v11, -v7, v10, v9
	v_fmac_f32_e32 v10, v11, v8
	v_fma_f32 v7, -v7, v10, v9
	v_div_fmas_f32 v7, v7, v8, v10
	v_div_fixup_f32 v5, v7, v6, v5
	ds_write_b32 v3, v5
	v_add_u32_e32 v3, 0x400, v3
	s_waitcnt vmcnt(8)
	v_mov_b32_e32 v5, v207
	v_mul_f32_e32 v6, 0xbfb8aa3b, v5
	v_exp_f32_e32 v6, v6
	s_nop 0
	v_add_f32_e32 v6, 1.0, v6
	v_div_scale_f32 v7, s[26:27], v6, v6, v5
	v_rcp_f32_e32 v8, v7
	v_div_scale_f32 v9, vcc, v5, v6, v5
	v_fma_f32 v10, -v7, v8, 1.0
	v_fmac_f32_e32 v8, v10, v8
	v_mul_f32_e32 v10, v9, v8
	v_fma_f32 v11, -v7, v10, v9
	v_fmac_f32_e32 v10, v11, v8
	v_fma_f32 v7, -v7, v10, v9
	v_div_fmas_f32 v7, v7, v8, v10
	v_div_fixup_f32 v5, v7, v6, v5
	ds_write_b32 v3, v5
	v_add_u32_e32 v3, 0x400, v3
	s_waitcnt vmcnt(7)
; DI void phase0(const Params& p, unsigned char* smem, const int tid, const int vb, const int nvb) {
;     ...
;             for (int i = tid; i < 4096; i += 256) { float v = p.in[1][i]; sc[i] = v / (1.f + __expf(-v)); }
;             __syncthreads();
;             const int col = tid & 15, kg = tid >> 4, n0 = a * 16;
;             float a0 = 0, a1 = 0, a2 = 0, a3 = 0;
;             const float* wp = p.in[2] + (size_t)(kg * 64) * 6144 + n0 + col;
	v_mov_b32_e32 v5, v208
	v_mul_f32_e32 v6, 0xbfb8aa3b, v5
	v_exp_f32_e32 v6, v6
	s_nop 0
	v_add_f32_e32 v6, 1.0, v6
	v_div_scale_f32 v7, s[26:27], v6, v6, v5
	v_rcp_f32_e32 v8, v7
	v_div_scale_f32 v9, vcc, v5, v6, v5
	v_fma_f32 v10, -v7, v8, 1.0
	v_fmac_f32_e32 v8, v10, v8
	v_mul_f32_e32 v10, v9, v8
	v_fma_f32 v11, -v7, v10, v9
	v_fmac_f32_e32 v10, v11, v8
	v_fma_f32 v7, -v7, v10, v9
	v_div_fmas_f32 v7, v7, v8, v10
	v_div_fixup_f32 v5, v7, v6, v5
	ds_write_b32 v3, v5
	v_add_u32_e32 v3, 0x400, v3
	s_waitcnt vmcnt(6)
	v_mov_b32_e32 v5, v209
	v_mul_f32_e32 v6, 0xbfb8aa3b, v5
	v_exp_f32_e32 v6, v6
	s_nop 0
	v_add_f32_e32 v6, 1.0, v6
	v_div_scale_f32 v7, s[26:27], v6, v6, v5
	v_rcp_f32_e32 v8, v7
	v_div_scale_f32 v9, vcc, v5, v6, v5
	v_fma_f32 v10, -v7, v8, 1.0
	v_fmac_f32_e32 v8, v10, v8
	v_mul_f32_e32 v10, v9, v8
	v_fma_f32 v11, -v7, v10, v9
	v_fmac_f32_e32 v10, v11, v8
	v_fma_f32 v7, -v7, v10, v9
	v_div_fmas_f32 v7, v7, v8, v10
	v_div_fixup_f32 v5, v7, v6, v5
	ds_write_b32 v3, v5
	v_add_u32_e32 v3, 0x400, v3
	s_waitcnt vmcnt(5)
	v_mov_b32_e32 v5, v210
	v_mul_f32_e32 v6, 0xbfb8aa3b, v5
	v_exp_f32_e32 v6, v6
	s_nop 0
	v_add_f32_e32 v6, 1.0, v6
	v_div_scale_f32 v7, s[26:27], v6, v6, v5
	v_rcp_f32_e32 v8, v7
	v_div_scale_f32 v9, vcc, v5, v6, v5
	v_fma_f32 v10, -v7, v8, 1.0
	v_fmac_f32_e32 v8, v10, v8
	v_mul_f32_e32 v10, v9, v8
	v_fma_f32 v11, -v7, v10, v9
	v_fmac_f32_e32 v10, v11, v8
	v_fma_f32 v7, -v7, v10, v9
	v_div_fmas_f32 v7, v7, v8, v10
	v_div_fixup_f32 v5, v7, v6, v5
	ds_write_b32 v3, v5
	v_add_u32_e32 v3, 0x400, v3
	s_waitcnt vmcnt(4)
	v_mov_b32_e32 v5, v211
	v_mul_f32_e32 v6, 0xbfb8aa3b, v5
	v_exp_f32_e32 v6, v6
	s_nop 0
	v_add_f32_e32 v6, 1.0, v6
	v_div_scale_f32 v7, s[26:27], v6, v6, v5
	v_rcp_f32_e32 v8, v7
	v_div_scale_f32 v9, vcc, v5, v6, v5
	v_fma_f32 v10, -v7, v8, 1.0
	v_fmac_f32_e32 v8, v10, v8
	v_mul_f32_e32 v10, v9, v8
	v_fma_f32 v11, -v7, v10, v9
	v_fmac_f32_e32 v10, v11, v8
	v_fma_f32 v7, -v7, v10, v9
	v_div_fmas_f32 v7, v7, v8, v10
	v_div_fixup_f32 v5, v7, v6, v5
	ds_write_b32 v3, v5
	v_add_u32_e32 v3, 0x400, v3
	s_waitcnt vmcnt(3)
	v_mov_b32_e32 v5, v212
	v_mul_f32_e32 v6, 0xbfb8aa3b, v5
	v_exp_f32_e32 v6, v6
	s_nop 0
	v_add_f32_e32 v6, 1.0, v6
	v_div_scale_f32 v7, s[26:27], v6, v6, v5
	v_rcp_f32_e32 v8, v7
	v_div_scale_f32 v9, vcc, v5, v6, v5
	v_fma_f32 v10, -v7, v8, 1.0
	v_fmac_f32_e32 v8, v10, v8
	v_mul_f32_e32 v10, v9, v8
	v_fma_f32 v11, -v7, v10, v9
	v_fmac_f32_e32 v10, v11, v8
	v_fma_f32 v7, -v7, v10, v9
	v_div_fmas_f32 v7, v7, v8, v10
	v_div_fixup_f32 v5, v7, v6, v5
	ds_write_b32 v3, v5
	v_add_u32_e32 v3, 0x400, v3
	s_waitcnt vmcnt(2)
	v_mov_b32_e32 v5, v213
	v_mul_f32_e32 v6, 0xbfb8aa3b, v5
	v_exp_f32_e32 v6, v6
	s_nop 0
	v_add_f32_e32 v6, 1.0, v6
	v_div_scale_f32 v7, s[26:27], v6, v6, v5
	v_rcp_f32_e32 v8, v7
	v_div_scale_f32 v9, vcc, v5, v6, v5
	v_fma_f32 v10, -v7, v8, 1.0
	v_fmac_f32_e32 v8, v10, v8
	v_mul_f32_e32 v10, v9, v8
	v_fma_f32 v11, -v7, v10, v9
	v_fmac_f32_e32 v10, v11, v8
	v_fma_f32 v7, -v7, v10, v9
	v_div_fmas_f32 v7, v7, v8, v10
	v_div_fixup_f32 v5, v7, v6, v5
	ds_write_b32 v3, v5
	v_add_u32_e32 v3, 0x400, v3
	s_waitcnt vmcnt(1)
	v_mov_b32_e32 v5, v214
	v_mul_f32_e32 v6, 0xbfb8aa3b, v5
	v_exp_f32_e32 v6, v6
	s_nop 0
	v_add_f32_e32 v6, 1.0, v6
	v_div_scale_f32 v7, s[26:27], v6, v6, v5
	v_rcp_f32_e32 v8, v7
	v_div_scale_f32 v9, vcc, v5, v6, v5
	v_fma_f32 v10, -v7, v8, 1.0
	v_fmac_f32_e32 v8, v10, v8
	v_mul_f32_e32 v10, v9, v8
	v_fma_f32 v11, -v7, v10, v9
	v_fmac_f32_e32 v10, v11, v8
	v_fma_f32 v7, -v7, v10, v9
	v_div_fmas_f32 v7, v7, v8, v10
	v_div_fixup_f32 v5, v7, v6, v5
	ds_write_b32 v3, v5
	v_add_u32_e32 v3, 0x400, v3
	s_waitcnt vmcnt(0)
	v_mov_b32_e32 v5, v215
	v_mul_f32_e32 v6, 0xbfb8aa3b, v5
	v_exp_f32_e32 v6, v6
	s_nop 0
	v_add_f32_e32 v6, 1.0, v6
	v_div_scale_f32 v7, s[26:27], v6, v6, v5
	v_rcp_f32_e32 v8, v7
	v_div_scale_f32 v9, vcc, v5, v6, v5
	v_fma_f32 v10, -v7, v8, 1.0
	v_fmac_f32_e32 v8, v10, v8
	v_mul_f32_e32 v10, v9, v8
	v_fma_f32 v11, -v7, v10, v9
	v_fmac_f32_e32 v10, v11, v8
	v_fma_f32 v7, -v7, v10, v9
	v_div_fmas_f32 v7, v7, v8, v10
	v_div_fixup_f32 v5, v7, v6, v5
	ds_write_b32 v3, v5
	v_add_u32_e32 v3, 0x400, v3
	s_or_b64 exec, exec, s[24:25]
	v_lshl_add_u32 v68, v4, 4, v126
	v_mov_b32_e32 v102, 0
	v_lshl_add_u64 v[100:101], v[68:69], 2, v[96:97]
	s_mov_b64 s[24:25], 0
	v_mov_b32_e32 v129, v109
	v_mov_b32_e32 v103, v102
	v_mov_b32_e32 v104, v102
	v_mov_b32_e32 v105, v102
	s_waitcnt lgkmcnt(0)
	s_barrier
; DI void phase0(const Params& p, unsigned char* smem, const int tid, const int vb, const int nvb) {
;     ...
;             const float* wp = p.in[2] + (size_t)(kg * 64) * 6144 + n0 + col;
; #pragma unroll 16
;             for (int k = 0; k < 64; ++k) {
;                 float w = wp[(size_t)k * 6144];
;                 int kk = kg * 64 + k;
;                 a0 += sc[kk] * w; a1 += sc[1024 + kk] * w; a2 += sc[2048 + kk] * w; a3 += sc[3072 + kk] * w;
;             }
.LBB0_33:
	s_mov_b64 s[26:27], 0x6000
	v_mov_b64_e32 v[232:233], v[100:101]
	global_load_dword v164, v[232:233], off
	v_lshl_add_u64 v[232:233], v[232:233], 0, s[26:27]
	global_load_dword v165, v[232:233], off
	v_lshl_add_u64 v[232:233], v[232:233], 0, s[26:27]
	global_load_dword v166, v[232:233], off
	v_lshl_add_u64 v[232:233], v[232:233], 0, s[26:27]
	global_load_dword v167, v[232:233], off
	v_lshl_add_u64 v[232:233], v[232:233], 0, s[26:27]
	global_load_dword v168, v[232:233], off
	v_lshl_add_u64 v[232:233], v[232:233], 0, s[26:27]
	global_load_dword v169, v[232:233], off
	v_lshl_add_u64 v[232:233], v[232:233], 0, s[26:27]
	global_load_dword v170, v[232:233], off
	v_lshl_add_u64 v[232:233], v[232:233], 0, s[26:27]
	global_load_dword v171, v[232:233], off
	v_lshl_add_u64 v[232:233], v[232:233], 0, s[26:27]
	global_load_dword v172, v[232:233], off
	v_lshl_add_u64 v[232:233], v[232:233], 0, s[26:27]
	global_load_dword v173, v[232:233], off
	v_lshl_add_u64 v[232:233], v[232:233], 0, s[26:27]
	global_load_dword v174, v[232:233], off
	v_lshl_add_u64 v[232:233], v[232:233], 0, s[26:27]
	global_load_dword v175, v[232:233], off
	v_lshl_add_u64 v[232:233], v[232:233], 0, s[26:27]
	global_load_dword v176, v[232:233], off
	v_lshl_add_u64 v[232:233], v[232:233], 0, s[26:27]
	global_load_dword v177, v[232:233], off
	v_lshl_add_u64 v[232:233], v[232:233], 0, s[26:27]
	global_load_dword v178, v[232:233], off
	v_lshl_add_u64 v[232:233], v[232:233], 0, s[26:27]
	global_load_dword v179, v[232:233], off
	v_lshl_add_u64 v[232:233], v[232:233], 0, s[26:27]
	global_load_dword v180, v[232:233], off
	v_lshl_add_u64 v[232:233], v[232:233], 0, s[26:27]
	global_load_dword v181, v[232:233], off
	v_lshl_add_u64 v[232:233], v[232:233], 0, s[26:27]
	global_load_dword v182, v[232:233], off
	v_lshl_add_u64 v[232:233], v[232:233], 0, s[26:27]
	global_load_dword v183, v[232:233], off
	v_lshl_add_u64 v[232:233], v[232:233], 0, s[26:27]
	global_load_dword v184, v[232:233], off
	v_lshl_add_u64 v[232:233], v[232:233], 0, s[26:27]
	global_load_dword v185, v[232:233], off
	v_lshl_add_u64 v[232:233], v[232:233], 0, s[26:27]
	global_load_dword v186, v[232:233], off
	v_lshl_add_u64 v[232:233], v[232:233], 0, s[26:27]
	global_load_dword v187, v[232:233], off
	v_lshl_add_u64 v[232:233], v[232:233], 0, s[26:27]
	global_load_dword v188, v[232:233], off
	v_lshl_add_u64 v[232:233], v[232:233], 0, s[26:27]
	global_load_dword v189, v[232:233], off
	v_lshl_add_u64 v[232:233], v[232:233], 0, s[26:27]
	global_load_dword v190, v[232:233], off
	v_lshl_add_u64 v[232:233], v[232:233], 0, s[26:27]
	global_load_dword v191, v[232:233], off
	v_lshl_add_u64 v[232:233], v[232:233], 0, s[26:27]
	global_load_dword v192, v[232:233], off
	v_lshl_add_u64 v[232:233], v[232:233], 0, s[26:27]
	global_load_dword v193, v[232:233], off
	v_lshl_add_u64 v[232:233], v[232:233], 0, s[26:27]
	global_load_dword v194, v[232:233], off
	v_lshl_add_u64 v[232:233], v[232:233], 0, s[26:27]
	global_load_dword v195, v[232:233], off
	v_lshl_add_u64 v[232:233], v[232:233], 0, s[26:27]
	global_load_dword v196, v[232:233], off
	v_lshl_add_u64 v[232:233], v[232:233], 0, s[26:27]
	global_load_dword v197, v[232:233], off
	v_lshl_add_u64 v[232:233], v[232:233], 0, s[26:27]
	global_load_dword v198, v[232:233], off
	v_lshl_add_u64 v[232:233], v[232:233], 0, s[26:27]
	global_load_dword v199, v[232:233], off
	v_lshl_add_u64 v[232:233], v[232:233], 0, s[26:27]
	global_load_dword v200, v[232:233], off
	v_lshl_add_u64 v[232:233], v[232:233], 0, s[26:27]
	global_load_dword v201, v[232:233], off
	v_lshl_add_u64 v[232:233], v[232:233], 0, s[26:27]
	global_load_dword v202, v[232:233], off
	v_lshl_add_u64 v[232:233], v[232:233], 0, s[26:27]
	global_load_dword v203, v[232:233], off
	v_lshl_add_u64 v[232:233], v[232:233], 0, s[26:27]
	global_load_dword v204, v[232:233], off
	v_lshl_add_u64 v[232:233], v[232:233], 0, s[26:27]
	global_load_dword v205, v[232:233], off
	v_lshl_add_u64 v[232:233], v[232:233], 0, s[26:27]
	global_load_dword v206, v[232:233], off
	v_lshl_add_u64 v[232:233], v[232:233], 0, s[26:27]
	global_load_dword v207, v[232:233], off
	v_lshl_add_u64 v[232:233], v[232:233], 0, s[26:27]
	global_load_dword v208, v[232:233], off
	v_lshl_add_u64 v[232:233], v[232:233], 0, s[26:27]
	global_load_dword v209, v[232:233], off
	v_lshl_add_u64 v[232:233], v[232:233], 0, s[26:27]
	global_load_dword v210, v[232:233], off
	v_lshl_add_u64 v[232:233], v[232:233], 0, s[26:27]
	global_load_dword v211, v[232:233], off
	v_lshl_add_u64 v[232:233], v[232:233], 0, s[26:27]
	global_load_dword v212, v[232:233], off
	v_lshl_add_u64 v[232:233], v[232:233], 0, s[26:27]
	global_load_dword v213, v[232:233], off
	v_lshl_add_u64 v[232:233], v[232:233], 0, s[26:27]
	global_load_dword v214, v[232:233], off
	v_lshl_add_u64 v[232:233], v[232:233], 0, s[26:27]
	global_load_dword v215, v[232:233], off
	v_lshl_add_u64 v[232:233], v[232:233], 0, s[26:27]
	global_load_dword v216, v[232:233], off
	v_lshl_add_u64 v[232:233], v[232:233], 0, s[26:27]
	global_load_dword v217, v[232:233], off
	v_lshl_add_u64 v[232:233], v[232:233], 0, s[26:27]
	global_load_dword v218, v[232:233], off
	v_lshl_add_u64 v[232:233], v[232:233], 0, s[26:27]
	global_load_dword v219, v[232:233], off
	v_lshl_add_u64 v[232:233], v[232:233], 0, s[26:27]
	global_load_dword v220, v[232:233], off
	v_lshl_add_u64 v[232:233], v[232:233], 0, s[26:27]
	global_load_dword v221, v[232:233], off
	v_lshl_add_u64 v[232:233], v[232:233], 0, s[26:27]
	global_load_dword v222, v[232:233], off
	v_lshl_add_u64 v[232:233], v[232:233], 0, s[26:27]
	global_load_dword v223, v[232:233], off
	v_lshl_add_u64 v[232:233], v[232:233], 0, s[26:27]
	global_load_dword v224, v[232:233], off
	v_lshl_add_u64 v[232:233], v[232:233], 0, s[26:27]
	global_load_dword v225, v[232:233], off
	v_lshl_add_u64 v[232:233], v[232:233], 0, s[26:27]
	global_load_dword v226, v[232:233], off
	v_lshl_add_u64 v[232:233], v[232:233], 0, s[26:27]
	global_load_dword v227, v[232:233], off
	ds_read_b128 v[16:19], v129
	ds_read_b128 v[12:15], v129 offset:16
	ds_read_b128 v[8:11], v129 offset:32
	ds_read_b128 v[4:7], v129 offset:48
	ds_read_b128 v[0:3], v129 offset:4096
	ds_read_b128 v[20:23], v129 offset:4112
	ds_read_b128 v[36:39], v129 offset:8192
	ds_read_b128 v[32:35], v129 offset:8208
	ds_read_b128 v[28:31], v129 offset:12288
	ds_read_b128 v[24:27], v129 offset:12304
	ds_read_b128 v[40:43], v129 offset:4128
	ds_read_b128 v[44:47], v129 offset:4144
	ds_read_b128 v[60:63], v129 offset:8224
	ds_read_b128 v[56:59], v129 offset:8240
	ds_read_b128 v[52:55], v129 offset:12320
	ds_read_b128 v[48:51], v129 offset:12336
	s_waitcnt lgkmcnt(14)
; DI void phase0(const Params& p, unsigned char* smem, const int tid, const int vb, const int nvb) {
;     ...
; #pragma unroll 16
;             for (int k = 0; k < 64; ++k) {
;                 float w = wp[(size_t)k * 6144];
;                 int kk = kg * 64 + k;
;                 a0 += sc[kk] * w; a1 += sc[1024 + kk] * w; a2 += sc[2048 + kk] * w; a3 += sc[3072 + kk] * w;
;             }
	v_mov_b32_e32 v160, v16
	s_waitcnt lgkmcnt(11)
	v_mov_b32_e32 v161, v0
	s_waitcnt lgkmcnt(9)
	v_mov_b32_e32 v162, v36
	s_waitcnt lgkmcnt(7)
	v_mov_b32_e32 v163, v28
	v_mov_b32_e32 v0, v17
	v_mov_b32_e32 v28, v37
	v_mov_b32_e32 v16, v18
	v_mov_b32_e32 v17, v2
	v_mov_b32_e32 v36, v38
	v_mov_b32_e32 v37, v30
	v_mov_b32_e32 v2, v19
	v_mov_b32_e32 v30, v39
	v_mov_b32_e32 v18, v12
	v_mov_b32_e32 v19, v20
	v_mov_b32_e32 v38, v32
	s_waitcnt lgkmcnt(6)
	v_mov_b32_e32 v39, v24
	v_mov_b32_e32 v20, v13
	v_mov_b32_e32 v24, v33
	v_mov_b32_e32 v12, v14
	v_mov_b32_e32 v13, v22
	v_mov_b32_e32 v32, v34
	v_mov_b32_e32 v33, v26
	v_mov_b32_e32 v22, v15
	v_mov_b32_e32 v26, v35
	v_mov_b32_e32 v14, v8
	s_waitcnt lgkmcnt(5)
	v_mov_b32_e32 v15, v40
	s_waitcnt lgkmcnt(3)
	v_mov_b32_e32 v34, v60
	s_waitcnt lgkmcnt(1)
	v_mov_b32_e32 v35, v52
	v_mov_b32_e32 v40, v9
	v_mov_b32_e32 v52, v61
	v_mov_b32_e32 v8, v10
	v_mov_b32_e32 v9, v42
	v_mov_b32_e32 v60, v62
	v_mov_b32_e32 v61, v54
	v_mov_b32_e32 v42, v11
	v_mov_b32_e32 v54, v63
	v_mov_b32_e32 v10, v4
	v_mov_b32_e32 v11, v44
	v_mov_b32_e32 v62, v56
	s_waitcnt lgkmcnt(0)
	v_mov_b32_e32 v63, v48
	v_mov_b32_e32 v44, v5
	v_mov_b32_e32 v48, v57
	v_mov_b32_e32 v4, v6
	v_mov_b32_e32 v5, v46
	v_mov_b32_e32 v56, v58
	v_mov_b32_e32 v57, v50
	v_mov_b32_e32 v46, v7
	v_mov_b32_e32 v50, v59
	s_waitcnt vmcnt(48)
	v_mov_b32_e32 v130, v164
	v_mov_b32_e32 v132, v165
	v_mov_b32_e32 v134, v166
	v_mov_b32_e32 v136, v167
	v_mov_b32_e32 v138, v168
	v_mov_b32_e32 v140, v169
	v_mov_b32_e32 v142, v170
	v_mov_b32_e32 v144, v171
	v_mov_b32_e32 v146, v172
	v_mov_b32_e32 v148, v173
	v_mov_b32_e32 v150, v174
	v_mov_b32_e32 v152, v175
	v_mov_b32_e32 v154, v176
	v_mov_b32_e32 v156, v177
	v_mov_b32_e32 v158, v178
	v_mov_b32_e32 v106, v179
	v_pk_fma_f32 v[6:7], v[130:131], v[160:161], v[102:103] op_sel_hi:[0,1,1]
	v_pk_fma_f32 v[58:59], v[130:131], v[162:163], v[104:105] op_sel_hi:[0,1,1]
	s_add_u32 s24, s24, 0x60000
	s_addc_u32 s25, s25, 0
	v_add_u32_e32 v129, 64, v129
	s_cmp_eq_u32 s24, 0x180000
	v_pk_fma_f32 v[0:1], v[132:133], v[0:1], v[6:7] op_sel_hi:[0,1,1]
	v_pk_fma_f32 v[6:7], v[132:133], v[28:29], v[58:59] op_sel_hi:[0,1,1]
	v_pk_fma_f32 v[0:1], v[134:135], v[16:17], v[0:1] op_sel_hi:[0,1,1]
	v_pk_fma_f32 v[6:7], v[134:135], v[36:37], v[6:7] op_sel_hi:[0,1,1]
	v_pk_fma_f32 v[0:1], v[136:137], v[2:3], v[0:1] op_sel_hi:[0,1,1]
	v_pk_fma_f32 v[2:3], v[136:137], v[30:31], v[6:7] op_sel_hi:[0,1,1]
	v_pk_fma_f32 v[0:1], v[138:139], v[18:19], v[0:1] op_sel_hi:[0,1,1]
	v_pk_fma_f32 v[2:3], v[138:139], v[38:39], v[2:3] op_sel_hi:[0,1,1]
	v_pk_fma_f32 v[0:1], v[140:141], v[20:21], v[0:1] op_sel_hi:[0,1,1]
	v_pk_fma_f32 v[2:3], v[140:141], v[24:25], v[2:3] op_sel_hi:[0,1,1]
	v_pk_fma_f32 v[0:1], v[142:143], v[12:13], v[0:1] op_sel_hi:[0,1,1]
	v_pk_fma_f32 v[2:3], v[142:143], v[32:33], v[2:3] op_sel_hi:[0,1,1]
	v_pk_fma_f32 v[0:1], v[144:145], v[22:23], v[0:1] op_sel_hi:[0,1,1]
	v_pk_fma_f32 v[2:3], v[144:145], v[26:27], v[2:3] op_sel_hi:[0,1,1]
	v_pk_fma_f32 v[0:1], v[146:147], v[14:15], v[0:1] op_sel_hi:[0,1,1]
	v_pk_fma_f32 v[2:3], v[146:147], v[34:35], v[2:3] op_sel_hi:[0,1,1]
	v_pk_fma_f32 v[0:1], v[148:149], v[40:41], v[0:1] op_sel_hi:[0,1,1]
	v_pk_fma_f32 v[2:3], v[148:149], v[52:53], v[2:3] op_sel_hi:[0,1,1]
	v_pk_fma_f32 v[0:1], v[150:151], v[8:9], v[0:1] op_sel_hi:[0,1,1]
	v_pk_fma_f32 v[2:3], v[150:151], v[60:61], v[2:3] op_sel_hi:[0,1,1]
	v_pk_fma_f32 v[0:1], v[152:153], v[42:43], v[0:1] op_sel_hi:[0,1,1]
	v_pk_fma_f32 v[2:3], v[152:153], v[54:55], v[2:3] op_sel_hi:[0,1,1]
	v_pk_fma_f32 v[0:1], v[154:155], v[10:11], v[0:1] op_sel_hi:[0,1,1]
	v_pk_fma_f32 v[2:3], v[154:155], v[62:63], v[2:3] op_sel_hi:[0,1,1]
	v_pk_fma_f32 v[0:1], v[156:157], v[44:45], v[0:1] op_sel_hi:[0,1,1]
	v_pk_fma_f32 v[2:3], v[156:157], v[48:49], v[2:3] op_sel_hi:[0,1,1]
	v_pk_fma_f32 v[0:1], v[158:159], v[4:5], v[0:1] op_sel_hi:[0,1,1]
	v_pk_fma_f32 v[2:3], v[158:159], v[56:57], v[2:3] op_sel_hi:[0,1,1]
	v_pk_fma_f32 v[102:103], v[106:107], v[46:47], v[0:1] op_sel_hi:[0,1,1]
	v_pk_fma_f32 v[104:105], v[106:107], v[50:51], v[2:3] op_sel_hi:[0,1,1]
	ds_read_b128 v[16:19], v129
	ds_read_b128 v[12:15], v129 offset:16
	ds_read_b128 v[8:11], v129 offset:32
	ds_read_b128 v[4:7], v129 offset:48
	ds_read_b128 v[0:3], v129 offset:4096
	ds_read_b128 v[20:23], v129 offset:4112
	ds_read_b128 v[36:39], v129 offset:8192
	ds_read_b128 v[32:35], v129 offset:8208
	ds_read_b128 v[28:31], v129 offset:12288
	ds_read_b128 v[24:27], v129 offset:12304
	ds_read_b128 v[40:43], v129 offset:4128
	ds_read_b128 v[44:47], v129 offset:4144
	ds_read_b128 v[60:63], v129 offset:8224
	ds_read_b128 v[56:59], v129 offset:8240
	ds_read_b128 v[52:55], v129 offset:12320
	ds_read_b128 v[48:51], v129 offset:12336
	s_waitcnt lgkmcnt(14)
	v_mov_b32_e32 v160, v16
	s_waitcnt lgkmcnt(11)
	v_mov_b32_e32 v161, v0
	s_waitcnt lgkmcnt(9)
	v_mov_b32_e32 v162, v36
	s_waitcnt lgkmcnt(7)
	v_mov_b32_e32 v163, v28
	v_mov_b32_e32 v0, v17
	v_mov_b32_e32 v28, v37
	v_mov_b32_e32 v16, v18
	v_mov_b32_e32 v17, v2
	v_mov_b32_e32 v36, v38
	v_mov_b32_e32 v37, v30
	v_mov_b32_e32 v2, v19
	v_mov_b32_e32 v30, v39
	v_mov_b32_e32 v18, v12
	v_mov_b32_e32 v19, v20
	v_mov_b32_e32 v38, v32
	s_waitcnt lgkmcnt(6)
	v_mov_b32_e32 v39, v24
	v_mov_b32_e32 v20, v13
	v_mov_b32_e32 v24, v33
	v_mov_b32_e32 v12, v14
	v_mov_b32_e32 v13, v22
	v_mov_b32_e32 v32, v34
	v_mov_b32_e32 v33, v26
	v_mov_b32_e32 v22, v15
	v_mov_b32_e32 v26, v35
	v_mov_b32_e32 v14, v8
	s_waitcnt lgkmcnt(5)
	v_mov_b32_e32 v15, v40
	s_waitcnt lgkmcnt(3)
	v_mov_b32_e32 v34, v60
	s_waitcnt lgkmcnt(1)
; DI void phase0(const Params& p, unsigned char* smem, const int tid, const int vb, const int nvb) {
;     ...
; #pragma unroll 16
;             for (int k = 0; k < 64; ++k) {
;                 float w = wp[(size_t)k * 6144];
;                 int kk = kg * 64 + k;
;                 a0 += sc[kk] * w; a1 += sc[1024 + kk] * w; a2 += sc[2048 + kk] * w; a3 += sc[3072 + kk] * w;
;             }
	v_mov_b32_e32 v35, v52
	v_mov_b32_e32 v40, v9
	v_mov_b32_e32 v52, v61
	v_mov_b32_e32 v8, v10
	v_mov_b32_e32 v9, v42
	v_mov_b32_e32 v60, v62
	v_mov_b32_e32 v61, v54
	v_mov_b32_e32 v42, v11
	v_mov_b32_e32 v54, v63
	v_mov_b32_e32 v10, v4
	v_mov_b32_e32 v11, v44
	v_mov_b32_e32 v62, v56
	s_waitcnt lgkmcnt(0)
	v_mov_b32_e32 v63, v48
	v_mov_b32_e32 v44, v5
	v_mov_b32_e32 v48, v57
	v_mov_b32_e32 v4, v6
	v_mov_b32_e32 v5, v46
	v_mov_b32_e32 v56, v58
	v_mov_b32_e32 v57, v50
	v_mov_b32_e32 v46, v7
	v_mov_b32_e32 v50, v59
	s_waitcnt vmcnt(32)
	v_mov_b32_e32 v130, v180
	v_mov_b32_e32 v132, v181
	v_mov_b32_e32 v134, v182
	v_mov_b32_e32 v136, v183
	v_mov_b32_e32 v138, v184
	v_mov_b32_e32 v140, v185
	v_mov_b32_e32 v142, v186
	v_mov_b32_e32 v144, v187
	v_mov_b32_e32 v146, v188
	v_mov_b32_e32 v148, v189
	v_mov_b32_e32 v150, v190
	v_mov_b32_e32 v152, v191
	v_mov_b32_e32 v154, v192
	v_mov_b32_e32 v156, v193
	v_mov_b32_e32 v158, v194
	v_mov_b32_e32 v106, v195
	v_pk_fma_f32 v[6:7], v[130:131], v[160:161], v[102:103] op_sel_hi:[0,1,1]
	v_pk_fma_f32 v[58:59], v[130:131], v[162:163], v[104:105] op_sel_hi:[0,1,1]
	s_add_u32 s24, s24, 0x60000
	s_addc_u32 s25, s25, 0
	v_add_u32_e32 v129, 64, v129
	s_cmp_eq_u32 s24, 0x180000
	v_pk_fma_f32 v[0:1], v[132:133], v[0:1], v[6:7] op_sel_hi:[0,1,1]
	v_pk_fma_f32 v[6:7], v[132:133], v[28:29], v[58:59] op_sel_hi:[0,1,1]
	v_pk_fma_f32 v[0:1], v[134:135], v[16:17], v[0:1] op_sel_hi:[0,1,1]
	v_pk_fma_f32 v[6:7], v[134:135], v[36:37], v[6:7] op_sel_hi:[0,1,1]
	v_pk_fma_f32 v[0:1], v[136:137], v[2:3], v[0:1] op_sel_hi:[0,1,1]
	v_pk_fma_f32 v[2:3], v[136:137], v[30:31], v[6:7] op_sel_hi:[0,1,1]
	v_pk_fma_f32 v[0:1], v[138:139], v[18:19], v[0:1] op_sel_hi:[0,1,1]
	v_pk_fma_f32 v[2:3], v[138:139], v[38:39], v[2:3] op_sel_hi:[0,1,1]
	v_pk_fma_f32 v[0:1], v[140:141], v[20:21], v[0:1] op_sel_hi:[0,1,1]
	v_pk_fma_f32 v[2:3], v[140:141], v[24:25], v[2:3] op_sel_hi:[0,1,1]
	v_pk_fma_f32 v[0:1], v[142:143], v[12:13], v[0:1] op_sel_hi:[0,1,1]
	v_pk_fma_f32 v[2:3], v[142:143], v[32:33], v[2:3] op_sel_hi:[0,1,1]
	v_pk_fma_f32 v[0:1], v[144:145], v[22:23], v[0:1] op_sel_hi:[0,1,1]
	v_pk_fma_f32 v[2:3], v[144:145], v[26:27], v[2:3] op_sel_hi:[0,1,1]
	v_pk_fma_f32 v[0:1], v[146:147], v[14:15], v[0:1] op_sel_hi:[0,1,1]
	v_pk_fma_f32 v[2:3], v[146:147], v[34:35], v[2:3] op_sel_hi:[0,1,1]
	v_pk_fma_f32 v[0:1], v[148:149], v[40:41], v[0:1] op_sel_hi:[0,1,1]
	v_pk_fma_f32 v[2:3], v[148:149], v[52:53], v[2:3] op_sel_hi:[0,1,1]
	v_pk_fma_f32 v[0:1], v[150:151], v[8:9], v[0:1] op_sel_hi:[0,1,1]
	v_pk_fma_f32 v[2:3], v[150:151], v[60:61], v[2:3] op_sel_hi:[0,1,1]
	v_pk_fma_f32 v[0:1], v[152:153], v[42:43], v[0:1] op_sel_hi:[0,1,1]
	v_pk_fma_f32 v[2:3], v[152:153], v[54:55], v[2:3] op_sel_hi:[0,1,1]
	v_pk_fma_f32 v[0:1], v[154:155], v[10:11], v[0:1] op_sel_hi:[0,1,1]
	v_pk_fma_f32 v[2:3], v[154:155], v[62:63], v[2:3] op_sel_hi:[0,1,1]
	v_pk_fma_f32 v[0:1], v[156:157], v[44:45], v[0:1] op_sel_hi:[0,1,1]
	v_pk_fma_f32 v[2:3], v[156:157], v[48:49], v[2:3] op_sel_hi:[0,1,1]
	v_pk_fma_f32 v[0:1], v[158:159], v[4:5], v[0:1] op_sel_hi:[0,1,1]
	v_pk_fma_f32 v[2:3], v[158:159], v[56:57], v[2:3] op_sel_hi:[0,1,1]
	v_pk_fma_f32 v[102:103], v[106:107], v[46:47], v[0:1] op_sel_hi:[0,1,1]
	v_pk_fma_f32 v[104:105], v[106:107], v[50:51], v[2:3] op_sel_hi:[0,1,1]
	ds_read_b128 v[16:19], v129
	ds_read_b128 v[12:15], v129 offset:16
	ds_read_b128 v[8:11], v129 offset:32
	ds_read_b128 v[4:7], v129 offset:48
	ds_read_b128 v[0:3], v129 offset:4096
	ds_read_b128 v[20:23], v129 offset:4112
	ds_read_b128 v[36:39], v129 offset:8192
	ds_read_b128 v[32:35], v129 offset:8208
	ds_read_b128 v[28:31], v129 offset:12288
	ds_read_b128 v[24:27], v129 offset:12304
	ds_read_b128 v[40:43], v129 offset:4128
	ds_read_b128 v[44:47], v129 offset:4144
	ds_read_b128 v[60:63], v129 offset:8224
	ds_read_b128 v[56:59], v129 offset:8240
	ds_read_b128 v[52:55], v129 offset:12320
	ds_read_b128 v[48:51], v129 offset:12336
	s_waitcnt lgkmcnt(14)
	v_mov_b32_e32 v160, v16
	s_waitcnt lgkmcnt(11)
	v_mov_b32_e32 v161, v0
	s_waitcnt lgkmcnt(9)
	v_mov_b32_e32 v162, v36
	s_waitcnt lgkmcnt(7)
	v_mov_b32_e32 v163, v28
	v_mov_b32_e32 v0, v17
	v_mov_b32_e32 v28, v37
	v_mov_b32_e32 v16, v18
	v_mov_b32_e32 v17, v2
	v_mov_b32_e32 v36, v38
	v_mov_b32_e32 v37, v30
	v_mov_b32_e32 v2, v19
	v_mov_b32_e32 v30, v39
	v_mov_b32_e32 v18, v12
	v_mov_b32_e32 v19, v20
	v_mov_b32_e32 v38, v32
	s_waitcnt lgkmcnt(6)
	v_mov_b32_e32 v39, v24
	v_mov_b32_e32 v20, v13
	v_mov_b32_e32 v24, v33
	v_mov_b32_e32 v12, v14
	v_mov_b32_e32 v13, v22
	v_mov_b32_e32 v32, v34
	v_mov_b32_e32 v33, v26
	v_mov_b32_e32 v22, v15
	v_mov_b32_e32 v26, v35
	v_mov_b32_e32 v14, v8
	s_waitcnt lgkmcnt(5)
	v_mov_b32_e32 v15, v40
	s_waitcnt lgkmcnt(3)
	v_mov_b32_e32 v34, v60
	s_waitcnt lgkmcnt(1)
	v_mov_b32_e32 v35, v52
	v_mov_b32_e32 v40, v9
	v_mov_b32_e32 v52, v61
	v_mov_b32_e32 v8, v10
	v_mov_b32_e32 v9, v42
	v_mov_b32_e32 v60, v62
	v_mov_b32_e32 v61, v54
	v_mov_b32_e32 v42, v11
	v_mov_b32_e32 v54, v63
	v_mov_b32_e32 v10, v4
	v_mov_b32_e32 v11, v44
	v_mov_b32_e32 v62, v56
	s_waitcnt lgkmcnt(0)
	v_mov_b32_e32 v63, v48
	v_mov_b32_e32 v44, v5
	v_mov_b32_e32 v48, v57
	v_mov_b32_e32 v4, v6
	v_mov_b32_e32 v5, v46
	v_mov_b32_e32 v56, v58
	v_mov_b32_e32 v57, v50
	v_mov_b32_e32 v46, v7
	v_mov_b32_e32 v50, v59
	s_waitcnt vmcnt(16)
; DI void phase0(const Params& p, unsigned char* smem, const int tid, const int vb, const int nvb) {
;     ...
; #pragma unroll 16
;             for (int k = 0; k < 64; ++k) {
;                 float w = wp[(size_t)k * 6144];
;                 int kk = kg * 64 + k;
;                 a0 += sc[kk] * w; a1 += sc[1024 + kk] * w; a2 += sc[2048 + kk] * w; a3 += sc[3072 + kk] * w;
;             }
	v_mov_b32_e32 v130, v196
	v_mov_b32_e32 v132, v197
	v_mov_b32_e32 v134, v198
	v_mov_b32_e32 v136, v199
	v_mov_b32_e32 v138, v200
	v_mov_b32_e32 v140, v201
	v_mov_b32_e32 v142, v202
	v_mov_b32_e32 v144, v203
	v_mov_b32_e32 v146, v204
	v_mov_b32_e32 v148, v205
	v_mov_b32_e32 v150, v206
	v_mov_b32_e32 v152, v207
	v_mov_b32_e32 v154, v208
	v_mov_b32_e32 v156, v209
	v_mov_b32_e32 v158, v210
	v_mov_b32_e32 v106, v211
	v_pk_fma_f32 v[6:7], v[130:131], v[160:161], v[102:103] op_sel_hi:[0,1,1]
	v_pk_fma_f32 v[58:59], v[130:131], v[162:163], v[104:105] op_sel_hi:[0,1,1]
	s_add_u32 s24, s24, 0x60000
	s_addc_u32 s25, s25, 0
	v_add_u32_e32 v129, 64, v129
	s_cmp_eq_u32 s24, 0x180000
	v_pk_fma_f32 v[0:1], v[132:133], v[0:1], v[6:7] op_sel_hi:[0,1,1]
	v_pk_fma_f32 v[6:7], v[132:133], v[28:29], v[58:59] op_sel_hi:[0,1,1]
	v_pk_fma_f32 v[0:1], v[134:135], v[16:17], v[0:1] op_sel_hi:[0,1,1]
	v_pk_fma_f32 v[6:7], v[134:135], v[36:37], v[6:7] op_sel_hi:[0,1,1]
	v_pk_fma_f32 v[0:1], v[136:137], v[2:3], v[0:1] op_sel_hi:[0,1,1]
	v_pk_fma_f32 v[2:3], v[136:137], v[30:31], v[6:7] op_sel_hi:[0,1,1]
	v_pk_fma_f32 v[0:1], v[138:139], v[18:19], v[0:1] op_sel_hi:[0,1,1]
	v_pk_fma_f32 v[2:3], v[138:139], v[38:39], v[2:3] op_sel_hi:[0,1,1]
	v_pk_fma_f32 v[0:1], v[140:141], v[20:21], v[0:1] op_sel_hi:[0,1,1]
	v_pk_fma_f32 v[2:3], v[140:141], v[24:25], v[2:3] op_sel_hi:[0,1,1]
	v_pk_fma_f32 v[0:1], v[142:143], v[12:13], v[0:1] op_sel_hi:[0,1,1]
	v_pk_fma_f32 v[2:3], v[142:143], v[32:33], v[2:3] op_sel_hi:[0,1,1]
	v_pk_fma_f32 v[0:1], v[144:145], v[22:23], v[0:1] op_sel_hi:[0,1,1]
	v_pk_fma_f32 v[2:3], v[144:145], v[26:27], v[2:3] op_sel_hi:[0,1,1]
	v_pk_fma_f32 v[0:1], v[146:147], v[14:15], v[0:1] op_sel_hi:[0,1,1]
	v_pk_fma_f32 v[2:3], v[146:147], v[34:35], v[2:3] op_sel_hi:[0,1,1]
	v_pk_fma_f32 v[0:1], v[148:149], v[40:41], v[0:1] op_sel_hi:[0,1,1]
	v_pk_fma_f32 v[2:3], v[148:149], v[52:53], v[2:3] op_sel_hi:[0,1,1]
	v_pk_fma_f32 v[0:1], v[150:151], v[8:9], v[0:1] op_sel_hi:[0,1,1]
	v_pk_fma_f32 v[2:3], v[150:151], v[60:61], v[2:3] op_sel_hi:[0,1,1]
	v_pk_fma_f32 v[0:1], v[152:153], v[42:43], v[0:1] op_sel_hi:[0,1,1]
	v_pk_fma_f32 v[2:3], v[152:153], v[54:55], v[2:3] op_sel_hi:[0,1,1]
	v_pk_fma_f32 v[0:1], v[154:155], v[10:11], v[0:1] op_sel_hi:[0,1,1]
	v_pk_fma_f32 v[2:3], v[154:155], v[62:63], v[2:3] op_sel_hi:[0,1,1]
	v_pk_fma_f32 v[0:1], v[156:157], v[44:45], v[0:1] op_sel_hi:[0,1,1]
	v_pk_fma_f32 v[2:3], v[156:157], v[48:49], v[2:3] op_sel_hi:[0,1,1]
	v_pk_fma_f32 v[0:1], v[158:159], v[4:5], v[0:1] op_sel_hi:[0,1,1]
	v_pk_fma_f32 v[2:3], v[158:159], v[56:57], v[2:3] op_sel_hi:[0,1,1]
	v_pk_fma_f32 v[102:103], v[106:107], v[46:47], v[0:1] op_sel_hi:[0,1,1]
	v_pk_fma_f32 v[104:105], v[106:107], v[50:51], v[2:3] op_sel_hi:[0,1,1]
	ds_read_b128 v[16:19], v129
	ds_read_b128 v[12:15], v129 offset:16
	ds_read_b128 v[8:11], v129 offset:32
	ds_read_b128 v[4:7], v129 offset:48
	ds_read_b128 v[0:3], v129 offset:4096
	ds_read_b128 v[20:23], v129 offset:4112
	ds_read_b128 v[36:39], v129 offset:8192
	ds_read_b128 v[32:35], v129 offset:8208
	ds_read_b128 v[28:31], v129 offset:12288
	ds_read_b128 v[24:27], v129 offset:12304
	ds_read_b128 v[40:43], v129 offset:4128
	ds_read_b128 v[44:47], v129 offset:4144
	ds_read_b128 v[60:63], v129 offset:8224
	ds_read_b128 v[56:59], v129 offset:8240
	ds_read_b128 v[52:55], v129 offset:12320
	ds_read_b128 v[48:51], v129 offset:12336
	s_waitcnt lgkmcnt(14)
	v_mov_b32_e32 v160, v16
	s_waitcnt lgkmcnt(11)
	v_mov_b32_e32 v161, v0
	s_waitcnt lgkmcnt(9)
	v_mov_b32_e32 v162, v36
	s_waitcnt lgkmcnt(7)
	v_mov_b32_e32 v163, v28
	v_mov_b32_e32 v0, v17
	v_mov_b32_e32 v28, v37
	v_mov_b32_e32 v16, v18
	v_mov_b32_e32 v17, v2
	v_mov_b32_e32 v36, v38
	v_mov_b32_e32 v37, v30
	v_mov_b32_e32 v2, v19
	v_mov_b32_e32 v30, v39
	v_mov_b32_e32 v18, v12
	v_mov_b32_e32 v19, v20
	v_mov_b32_e32 v38, v32
	s_waitcnt lgkmcnt(6)
	v_mov_b32_e32 v39, v24
	v_mov_b32_e32 v20, v13
	v_mov_b32_e32 v24, v33
	v_mov_b32_e32 v12, v14
	v_mov_b32_e32 v13, v22
	v_mov_b32_e32 v32, v34
	v_mov_b32_e32 v33, v26
	v_mov_b32_e32 v22, v15
	v_mov_b32_e32 v26, v35
	v_mov_b32_e32 v14, v8
	s_waitcnt lgkmcnt(5)
	v_mov_b32_e32 v15, v40
	s_waitcnt lgkmcnt(3)
	v_mov_b32_e32 v34, v60
	s_waitcnt lgkmcnt(1)
	v_mov_b32_e32 v35, v52
	v_mov_b32_e32 v40, v9
	v_mov_b32_e32 v52, v61
	v_mov_b32_e32 v8, v10
	v_mov_b32_e32 v9, v42
	v_mov_b32_e32 v60, v62
	v_mov_b32_e32 v61, v54
	v_mov_b32_e32 v42, v11
	v_mov_b32_e32 v54, v63
	v_mov_b32_e32 v10, v4
	v_mov_b32_e32 v11, v44
	v_mov_b32_e32 v62, v56
	s_waitcnt lgkmcnt(0)
	v_mov_b32_e32 v63, v48
	v_mov_b32_e32 v44, v5
	v_mov_b32_e32 v48, v57
	v_mov_b32_e32 v4, v6
	v_mov_b32_e32 v5, v46
	v_mov_b32_e32 v56, v58
	v_mov_b32_e32 v57, v50
	v_mov_b32_e32 v46, v7
	v_mov_b32_e32 v50, v59
	s_waitcnt vmcnt(0)
; DI void phase0(const Params& p, unsigned char* smem, const int tid, const int vb, const int nvb) {
;     ...
; #pragma unroll 16
;             for (int k = 0; k < 64; ++k) {
;                 float w = wp[(size_t)k * 6144];
;                 int kk = kg * 64 + k;
;                 a0 += sc[kk] * w; a1 += sc[1024 + kk] * w; a2 += sc[2048 + kk] * w; a3 += sc[3072 + kk] * w;
;             }
;             red[(kg * 4 + 0) * 16 + col] = a0; red[(kg * 4 + 1) * 16 + col] = a1; red[(kg * 4 + 2) * 16 + col] = a2; red[(kg * 4 + 3) * 16 + col] = a3;
;             __syncthreads();
;             if (tid < 64) {
;                 int b = tid >> 4, c2 = tid & 15;
;                 float sacc = p.in[3][n0 + c2];
;                 for (int g = 0; g < 16; ++g) sacc += red[(g * 4 + b) * 16 + c2];
;                 ((float*)(ws + OFF_MOD))[b * 6144 + n0 + c2] = sacc;
;             }
	v_mov_b32_e32 v130, v212
	v_mov_b32_e32 v132, v213
	v_mov_b32_e32 v134, v214
	v_mov_b32_e32 v136, v215
	v_mov_b32_e32 v138, v216
	v_mov_b32_e32 v140, v217
	v_mov_b32_e32 v142, v218
	v_mov_b32_e32 v144, v219
	v_mov_b32_e32 v146, v220
	v_mov_b32_e32 v148, v221
	v_mov_b32_e32 v150, v222
	v_mov_b32_e32 v152, v223
	v_mov_b32_e32 v154, v224
	v_mov_b32_e32 v156, v225
	v_mov_b32_e32 v158, v226
	v_mov_b32_e32 v106, v227
	v_pk_fma_f32 v[6:7], v[130:131], v[160:161], v[102:103] op_sel_hi:[0,1,1]
	v_pk_fma_f32 v[58:59], v[130:131], v[162:163], v[104:105] op_sel_hi:[0,1,1]
	s_add_u32 s24, s24, 0x60000
	s_addc_u32 s25, s25, 0
	v_add_u32_e32 v129, 64, v129
	s_cmp_eq_u32 s24, 0x180000
	v_pk_fma_f32 v[0:1], v[132:133], v[0:1], v[6:7] op_sel_hi:[0,1,1]
	v_pk_fma_f32 v[6:7], v[132:133], v[28:29], v[58:59] op_sel_hi:[0,1,1]
	v_pk_fma_f32 v[0:1], v[134:135], v[16:17], v[0:1] op_sel_hi:[0,1,1]
	v_pk_fma_f32 v[6:7], v[134:135], v[36:37], v[6:7] op_sel_hi:[0,1,1]
	v_pk_fma_f32 v[0:1], v[136:137], v[2:3], v[0:1] op_sel_hi:[0,1,1]
	v_pk_fma_f32 v[2:3], v[136:137], v[30:31], v[6:7] op_sel_hi:[0,1,1]
	v_pk_fma_f32 v[0:1], v[138:139], v[18:19], v[0:1] op_sel_hi:[0,1,1]
	v_pk_fma_f32 v[2:3], v[138:139], v[38:39], v[2:3] op_sel_hi:[0,1,1]
	v_pk_fma_f32 v[0:1], v[140:141], v[20:21], v[0:1] op_sel_hi:[0,1,1]
	v_pk_fma_f32 v[2:3], v[140:141], v[24:25], v[2:3] op_sel_hi:[0,1,1]
	v_pk_fma_f32 v[0:1], v[142:143], v[12:13], v[0:1] op_sel_hi:[0,1,1]
	v_pk_fma_f32 v[2:3], v[142:143], v[32:33], v[2:3] op_sel_hi:[0,1,1]
	v_pk_fma_f32 v[0:1], v[144:145], v[22:23], v[0:1] op_sel_hi:[0,1,1]
	v_pk_fma_f32 v[2:3], v[144:145], v[26:27], v[2:3] op_sel_hi:[0,1,1]
	v_pk_fma_f32 v[0:1], v[146:147], v[14:15], v[0:1] op_sel_hi:[0,1,1]
	v_pk_fma_f32 v[2:3], v[146:147], v[34:35], v[2:3] op_sel_hi:[0,1,1]
	v_pk_fma_f32 v[0:1], v[148:149], v[40:41], v[0:1] op_sel_hi:[0,1,1]
	v_pk_fma_f32 v[2:3], v[148:149], v[52:53], v[2:3] op_sel_hi:[0,1,1]
	v_pk_fma_f32 v[0:1], v[150:151], v[8:9], v[0:1] op_sel_hi:[0,1,1]
	v_pk_fma_f32 v[2:3], v[150:151], v[60:61], v[2:3] op_sel_hi:[0,1,1]
	v_pk_fma_f32 v[0:1], v[152:153], v[42:43], v[0:1] op_sel_hi:[0,1,1]
	v_pk_fma_f32 v[2:3], v[152:153], v[54:55], v[2:3] op_sel_hi:[0,1,1]
	v_pk_fma_f32 v[0:1], v[154:155], v[10:11], v[0:1] op_sel_hi:[0,1,1]
	v_pk_fma_f32 v[2:3], v[154:155], v[62:63], v[2:3] op_sel_hi:[0,1,1]
	v_pk_fma_f32 v[0:1], v[156:157], v[44:45], v[0:1] op_sel_hi:[0,1,1]
	v_pk_fma_f32 v[2:3], v[156:157], v[48:49], v[2:3] op_sel_hi:[0,1,1]
	v_pk_fma_f32 v[0:1], v[158:159], v[4:5], v[0:1] op_sel_hi:[0,1,1]
	v_pk_fma_f32 v[2:3], v[158:159], v[56:57], v[2:3] op_sel_hi:[0,1,1]
	v_pk_fma_f32 v[102:103], v[106:107], v[46:47], v[0:1] op_sel_hi:[0,1,1]
	v_pk_fma_f32 v[104:105], v[106:107], v[50:51], v[2:3] op_sel_hi:[0,1,1]
	v_add_u32_e32 v0, 0x4000, v110
	ds_write2_b32 v0, v102, v103 offset1:16
	ds_write2_b32 v0, v104, v105 offset0:32 offset1:48
	s_waitcnt lgkmcnt(0)
	s_barrier
	s_and_saveexec_b64 s[24:25], s[0:1]
	s_cbranch_execz .LBB0_36
	v_readlane_b32 s72, v254, 4
	v_or_b32_e32 v0, v68, v108
	v_mov_b32_e32 v1, v69
	v_readlane_b32 s78, v254, 10
	v_readlane_b32 s79, v254, 11
	v_readlane_b32 s73, v254, 5
	v_readlane_b32 s74, v254, 6
	v_lshl_add_u64 v[0:1], v[0:1], 2, s[78:79]
	global_load_dword v16, v[0:1], off
	ds_read2st64_b32 v[0:1], v128 offset0:64 offset1:65
	ds_read2st64_b32 v[2:3], v128 offset0:66 offset1:67
	ds_read2st64_b32 v[4:5], v128 offset0:68 offset1:69
	ds_read2st64_b32 v[6:7], v128 offset0:70 offset1:71
	ds_read2st64_b32 v[8:9], v128 offset0:72 offset1:73
	ds_read2st64_b32 v[10:11], v128 offset0:74 offset1:75
	ds_read2st64_b32 v[12:13], v128 offset0:76 offset1:77
	ds_read2st64_b32 v[14:15], v128 offset0:78 offset1:79
	v_readlane_b32 s75, v254, 7
	v_readlane_b32 s76, v254, 8
	v_readlane_b32 s77, v254, 9
	v_readlane_b32 s80, v254, 12
	v_readlane_b32 s81, v254, 13
	v_readlane_b32 s82, v254, 14
	v_readlane_b32 s83, v254, 15
	v_readlane_b32 s84, v254, 16
	v_readlane_b32 s85, v254, 17
	v_readlane_b32 s86, v254, 18
	v_readlane_b32 s87, v254, 19
	v_readlane_b32 s72, v254, 36
	v_add_u32_e32 v68, v111, v68
	v_readlane_b32 s73, v254, 37
	v_readlane_b32 s74, v254, 38
	v_readlane_b32 s75, v254, 39
	v_readlane_b32 s80, v254, 44
	v_readlane_b32 s81, v254, 45
	v_readlane_b32 s82, v254, 46
	v_readlane_b32 s83, v254, 47
	v_readlane_b32 s84, v254, 48
	v_readlane_b32 s85, v254, 49
	v_readlane_b32 s86, v254, 50
	v_readlane_b32 s87, v254, 51
	v_readlane_b32 s76, v254, 40
	v_readlane_b32 s77, v254, 41
	v_readlane_b32 s78, v254, 42
	v_readlane_b32 s79, v254, 43
	s_waitcnt vmcnt(0) lgkmcnt(7)
	v_add_f32_e32 v0, v16, v0
	v_add_f32_e32 v0, v0, v1
	s_waitcnt lgkmcnt(6)
	v_add_f32_e32 v0, v0, v2
	v_add_f32_e32 v0, v0, v3
	s_waitcnt lgkmcnt(5)
	v_add_f32_e32 v0, v0, v4
	v_add_f32_e32 v0, v0, v5
	s_waitcnt lgkmcnt(4)
	v_add_f32_e32 v0, v0, v6
	v_add_f32_e32 v0, v0, v7
	s_waitcnt lgkmcnt(3)
	v_add_f32_e32 v0, v0, v8
	v_add_f32_e32 v0, v0, v9
	s_waitcnt lgkmcnt(2)
	v_add_f32_e32 v0, v0, v10
	v_add_f32_e32 v0, v0, v11
	s_waitcnt lgkmcnt(1)
	v_add_f32_e32 v0, v0, v12
	v_add_f32_e32 v0, v0, v13
	s_waitcnt lgkmcnt(0)
	v_add_f32_e32 v0, v0, v14
	v_add_f32_e32 v2, v0, v15
	v_lshl_add_u64 v[0:1], v[68:69], 2, s[12:13]
	global_store_dword v[0:1], v2, off

; DI void transpose_tile(unsigned char* smem, const int tid, const float* src, int K, int N, bf16_t* dst, int ldd, int permid, int kt, int nt) {
;     float (*tile)[65] = (float (*)[65])smem;
;     const int k0 = kt * 64, n0 = nt * 64;
;     float tv[16];
; #pragma unroll
;     for (int i = 0; i < 16; ++i) {
;         int kk = i * 4 + (tid >> 6), nn = tid & 63;
;         tv[i] = (n0 + nn < N) ? src[(size_t)(k0 + kk) * N + n0 + nn] : 0.f;
;     }
; #pragma unroll
;     for (int i = 0; i < 16; ++i) tile[tid & 63][i * 4 + (tid >> 6)] = tv[i];
; DI void phase0(const Params& p, unsigned char* smem, const int tid, const int vb, const int nvb) {
;     ...
;             if (id < 256) { transpose_tile(smem, tid, p.in[21], 1024, 1024, (bf16_t*)(ws + OFF_WMX), 1024, 0, id >> 4, id & 15); continue; }
.LBB0_61:
	s_andn2_saveexec_b64 s[4:5], s[34:35]
	s_cbranch_execz .LBB0_65
	v_lshrrev_b32_e32 v191, 4, v64
	v_and_b32_e32 v197, 15, v64
	s_mov_b64 s[88:89], 0x4000
	v_lshlrev_b32_e32 v196, 6, v191
	v_readfirstlane_b32 s91, v4
	v_add_u32_e32 v190, 0xfffff930, v4
	v_and_b32_e32 v189, 15, v190
	v_lshrrev_b32_e32 v188, 4, v190
	v_lshlrev_b32_e32 v190, 6, v189
	v_lshlrev_b32_e32 v192, 6, v188
	v_lshl_add_u32 v198, v66, 4, v190
	v_add_u32_e32 v193, v192, v191
	v_mul_u32_u24_e32 v193, 0x400, v193
	v_add_lshl_u32 v193, v193, v198, 2
	v_sub_u32_e32 v193, v193, v196
	v_add_co_u32_e32 v194, vcc, v88, v193
	v_readfirstlane_b32 s92, v198
	v_add_lshl_u32 v199, v192, v64, 1
	v_addc_co_u32_e32 v195, vcc, 0, v89, vcc
	global_load_dword v164, v[194:195], off
	v_lshl_add_u64 v[194:195], v[194:195], 0, s[88:89]
	global_load_dword v165, v[194:195], off
	v_lshl_add_u64 v[194:195], v[194:195], 0, s[88:89]
	global_load_dword v166, v[194:195], off
	v_lshl_add_u64 v[194:195], v[194:195], 0, s[88:89]
	global_load_dword v167, v[194:195], off
	v_lshl_add_u64 v[194:195], v[194:195], 0, s[88:89]
	global_load_dword v168, v[194:195], off
	v_lshl_add_u64 v[194:195], v[194:195], 0, s[88:89]
	global_load_dword v169, v[194:195], off
	v_lshl_add_u64 v[194:195], v[194:195], 0, s[88:89]
	global_load_dword v170, v[194:195], off
	v_lshl_add_u64 v[194:195], v[194:195], 0, s[88:89]
	global_load_dword v171, v[194:195], off
	v_lshl_add_u64 v[194:195], v[194:195], 0, s[88:89]
	global_load_dword v172, v[194:195], off
	v_lshl_add_u64 v[194:195], v[194:195], 0, s[88:89]
	global_load_dword v173, v[194:195], off
	v_lshl_add_u64 v[194:195], v[194:195], 0, s[88:89]
	global_load_dword v174, v[194:195], off
	v_lshl_add_u64 v[194:195], v[194:195], 0, s[88:89]
	global_load_dword v175, v[194:195], off
	v_lshl_add_u64 v[194:195], v[194:195], 0, s[88:89]
	global_load_dword v176, v[194:195], off
	v_lshl_add_u64 v[194:195], v[194:195], 0, s[88:89]
	global_load_dword v177, v[194:195], off
	v_lshl_add_u64 v[194:195], v[194:195], 0, s[88:89]
	global_load_dword v178, v[194:195], off
	v_lshl_add_u64 v[194:195], v[194:195], 0, s[88:89]
	global_load_dword v179, v[194:195], off
	s_add_i32 s91, s91, 0x200
	s_mov_b32 s98, 0
	s_cmpk_gt_u32 s91, 0x7cf
	s_cbranch_scc1 .Lp0t_mx_l1
	v_add_u32_e32 v224, 0xfffffb30, v4
	v_and_b32_e32 v223, 15, v224
	v_lshrrev_b32_e32 v222, 4, v224
	v_lshlrev_b32_e32 v224, 6, v223
	v_lshlrev_b32_e32 v220, 6, v222
	v_lshl_add_u32 v226, v66, 4, v224
	v_add_u32_e32 v225, v220, v191
	v_mul_u32_u24_e32 v225, 0x400, v225
	v_add_lshl_u32 v225, v225, v226, 2
	v_sub_u32_e32 v225, v225, v196
	v_add_co_u32_e32 v216, vcc, v88, v225
	v_readfirstlane_b32 s100, v226
	v_add_lshl_u32 v221, v220, v64, 1
	v_addc_co_u32_e32 v217, vcc, 0, v89, vcc
	global_load_dword v200, v[216:217], off
	v_lshl_add_u64 v[216:217], v[216:217], 0, s[88:89]
	global_load_dword v201, v[216:217], off
	v_lshl_add_u64 v[216:217], v[216:217], 0, s[88:89]
	global_load_dword v202, v[216:217], off
	v_lshl_add_u64 v[216:217], v[216:217], 0, s[88:89]
	global_load_dword v203, v[216:217], off
	v_lshl_add_u64 v[216:217], v[216:217], 0, s[88:89]
	global_load_dword v204, v[216:217], off
	v_lshl_add_u64 v[216:217], v[216:217], 0, s[88:89]
	global_load_dword v205, v[216:217], off
	v_lshl_add_u64 v[216:217], v[216:217], 0, s[88:89]
	global_load_dword v206, v[216:217], off
	v_lshl_add_u64 v[216:217], v[216:217], 0, s[88:89]
	global_load_dword v207, v[216:217], off
	v_lshl_add_u64 v[216:217], v[216:217], 0, s[88:89]
	global_load_dword v208, v[216:217], off
	v_lshl_add_u64 v[216:217], v[216:217], 0, s[88:89]
	global_load_dword v209, v[216:217], off
	v_lshl_add_u64 v[216:217], v[216:217], 0, s[88:89]
	global_load_dword v210, v[216:217], off
	v_lshl_add_u64 v[216:217], v[216:217], 0, s[88:89]
	global_load_dword v211, v[216:217], off
	v_lshl_add_u64 v[216:217], v[216:217], 0, s[88:89]
	global_load_dword v212, v[216:217], off
	v_lshl_add_u64 v[216:217], v[216:217], 0, s[88:89]
	global_load_dword v213, v[216:217], off
	v_lshl_add_u64 v[216:217], v[216:217], 0, s[88:89]
	global_load_dword v214, v[216:217], off
	v_lshl_add_u64 v[216:217], v[216:217], 0, s[88:89]
	global_load_dword v215, v[216:217], off
.Lp0t_mx_l1:
	v_lshrrev_b32_e32 v186, 8, v250
	v_mul_u32_u24_e32 v195, 0x1100, v66
	v_lshlrev_b32_e32 v186, 16, v186
	v_mul_u32_u24_e32 v187, 0x110, v197
	v_add_u32_e32 v186, v186, v195
	v_lshl_add_u32 v195, v191, 2, v187
	v_add_u32_e32 v186, 0x8010, v186
	v_lshl_add_u32 v187, v64, 2, v186
	v_add_u32_e32 v195, v195, v186
	s_cmpk_gt_u32 s91, 0x7cf
	s_cbranch_scc1 .Lp0t_mx_w1
	s_waitcnt vmcnt(16)
	s_branch .Lp0t_mx_w2

; DI unsigned short f2bf(float x) { return (unsigned short)(pk2(x, 0.f) & 0xffffu); }
; DI void transpose_tile(unsigned char* smem, const int tid, const float* src, int K, int N, bf16_t* dst, int ldd, int permid, int kt, int nt) {
;     ...
; #pragma unroll 4
;     for (int i = 0; i < 16; ++i) {
;         int nn = i * 4 + (tid >> 6), kk = tid & 63;
;         int n = n0 + nn;
;         if (n < N) {
;             int row = n;
;             if (permid == 1) row = (n < 2048) ? n : ((n >= 2056) ? n - 8 : -1);
;             else if (permid == 2) row = (n < 1024) ? ((n >> 2) * 8 + (n & 3)) : (((n - 1024) >> 2) * 8 + 4 + (n & 3));
;             else if (permid == 3) row = (n < 2816) ? ((n >> 2) * 8 + (n & 3)) : (((n - 2816) >> 2) * 8 + 4 + (n & 3));
;             if (row >= 0) dst[(size_t)row * ldd + k0 + kk] = f2bf(tile[nn][kk]);
;         }
;     }
.Lp0t_mx_w2:
	ds_write2_b32 v195, v164, v165 offset0:0 offset1:4
	ds_write2_b32 v195, v166, v167 offset0:8 offset1:12
	ds_write2_b32 v195, v168, v169 offset0:16 offset1:20
	ds_write2_b32 v195, v170, v171 offset0:24 offset1:28
	ds_write2_b32 v195, v172, v173 offset0:32 offset1:36
	ds_write2_b32 v195, v174, v175 offset0:40 offset1:44
	ds_write2_b32 v195, v176, v177 offset0:48 offset1:52
	ds_write2_b32 v195, v178, v179 offset0:56 offset1:60
	s_waitcnt lgkmcnt(0)
	ds_read_b32 v164, v187 offset:0
	ds_read_b32 v165, v187 offset:272
	ds_read_b32 v166, v187 offset:544
	ds_read_b32 v167, v187 offset:816
	ds_read_b32 v168, v187 offset:1088
	ds_read_b32 v169, v187 offset:1360
	ds_read_b32 v170, v187 offset:1632
	ds_read_b32 v171, v187 offset:1904
	ds_read_b32 v172, v187 offset:2176
	ds_read_b32 v173, v187 offset:2448
	ds_read_b32 v174, v187 offset:2720
	ds_read_b32 v175, v187 offset:2992
	ds_read_b32 v176, v187 offset:3264
	ds_read_b32 v177, v187 offset:3536
	ds_read_b32 v178, v187 offset:3808
	ds_read_b32 v179, v187 offset:4080
	s_add_i32 s93, s92, 0
	s_mov_b32 s94, s93
	s_mul_i32 s94, s94, 0x800
	s_add_i32 s94, s94, 0xd80000
	s_waitcnt lgkmcnt(15)
	v_cvt_pk_bf16_f32 v180, v164, v164
	v_add_u32_e32 v228, s94, v199
	global_store_short v228, v180, s[70:71]
	s_add_i32 s93, s92, 1
	s_mov_b32 s94, s93
	s_mul_i32 s94, s94, 0x800
	s_add_i32 s94, s94, 0xd80000
	s_waitcnt lgkmcnt(14)
	v_cvt_pk_bf16_f32 v181, v165, v165
	v_add_u32_e32 v229, s94, v199
	global_store_short v229, v181, s[70:71]
	s_add_i32 s93, s92, 2
	s_mov_b32 s94, s93
	s_mul_i32 s94, s94, 0x800
	s_add_i32 s94, s94, 0xd80000
	s_waitcnt lgkmcnt(13)
	v_cvt_pk_bf16_f32 v182, v166, v166
	v_add_u32_e32 v230, s94, v199
	global_store_short v230, v182, s[70:71]
	s_add_i32 s93, s92, 3
	s_mov_b32 s94, s93
	s_mul_i32 s94, s94, 0x800
	s_add_i32 s94, s94, 0xd80000
	s_waitcnt lgkmcnt(12)
	v_cvt_pk_bf16_f32 v183, v167, v167
	v_add_u32_e32 v231, s94, v199
	global_store_short v231, v183, s[70:71]
	s_add_i32 s93, s92, 4
	s_mov_b32 s94, s93
	s_mul_i32 s94, s94, 0x800
	s_add_i32 s94, s94, 0xd80000
	s_waitcnt lgkmcnt(11)
	v_cvt_pk_bf16_f32 v184, v168, v168
	v_add_u32_e32 v228, s94, v199
	global_store_short v228, v184, s[70:71]
	s_add_i32 s93, s92, 5
	s_mov_b32 s94, s93
	s_mul_i32 s94, s94, 0x800
	s_add_i32 s94, s94, 0xd80000
	s_waitcnt lgkmcnt(10)
	v_cvt_pk_bf16_f32 v185, v169, v169
	v_add_u32_e32 v229, s94, v199
	global_store_short v229, v185, s[70:71]
	s_add_i32 s93, s92, 6
	s_mov_b32 s94, s93
	s_mul_i32 s94, s94, 0x800
	s_add_i32 s94, s94, 0xd80000
	s_waitcnt lgkmcnt(9)
	v_cvt_pk_bf16_f32 v180, v170, v170
	v_add_u32_e32 v230, s94, v199
	global_store_short v230, v180, s[70:71]
	s_add_i32 s93, s92, 7
	s_mov_b32 s94, s93
	s_mul_i32 s94, s94, 0x800
	s_add_i32 s94, s94, 0xd80000
	s_waitcnt lgkmcnt(8)
	v_cvt_pk_bf16_f32 v181, v171, v171
	v_add_u32_e32 v231, s94, v199
	global_store_short v231, v181, s[70:71]
	s_add_i32 s93, s92, 8
	s_mov_b32 s94, s93
	s_mul_i32 s94, s94, 0x800
	s_add_i32 s94, s94, 0xd80000
	s_waitcnt lgkmcnt(7)
	v_cvt_pk_bf16_f32 v182, v172, v172
	v_add_u32_e32 v228, s94, v199
	global_store_short v228, v182, s[70:71]
	s_add_i32 s93, s92, 9
	s_mov_b32 s94, s93
	s_mul_i32 s94, s94, 0x800
	s_add_i32 s94, s94, 0xd80000
	s_waitcnt lgkmcnt(6)
	v_cvt_pk_bf16_f32 v183, v173, v173
	v_add_u32_e32 v229, s94, v199
	global_store_short v229, v183, s[70:71]
	s_add_i32 s93, s92, 10
	s_mov_b32 s94, s93
	s_mul_i32 s94, s94, 0x800
	s_add_i32 s94, s94, 0xd80000
	s_waitcnt lgkmcnt(5)
	v_cvt_pk_bf16_f32 v184, v174, v174
	v_add_u32_e32 v230, s94, v199
	global_store_short v230, v184, s[70:71]
	s_add_i32 s93, s92, 11
	s_mov_b32 s94, s93
	s_mul_i32 s94, s94, 0x800
	s_add_i32 s94, s94, 0xd80000
	s_waitcnt lgkmcnt(4)
	v_cvt_pk_bf16_f32 v185, v175, v175
	v_add_u32_e32 v231, s94, v199
	global_store_short v231, v185, s[70:71]
	s_add_i32 s93, s92, 12
	s_mov_b32 s94, s93
	s_mul_i32 s94, s94, 0x800
	s_add_i32 s94, s94, 0xd80000
	s_waitcnt lgkmcnt(3)
	v_cvt_pk_bf16_f32 v180, v176, v176
	v_add_u32_e32 v228, s94, v199
	global_store_short v228, v180, s[70:71]
	s_add_i32 s93, s92, 13
	s_mov_b32 s94, s93
	s_mul_i32 s94, s94, 0x800
	s_add_i32 s94, s94, 0xd80000
	s_waitcnt lgkmcnt(2)
	v_cvt_pk_bf16_f32 v181, v177, v177
	v_add_u32_e32 v229, s94, v199
	global_store_short v229, v181, s[70:71]
	s_add_i32 s93, s92, 14
	s_mov_b32 s94, s93
	s_mul_i32 s94, s94, 0x800
	s_add_i32 s94, s94, 0xd80000
	s_waitcnt lgkmcnt(1)
	v_cvt_pk_bf16_f32 v182, v178, v178
	v_add_u32_e32 v230, s94, v199
	global_store_short v230, v182, s[70:71]
	s_add_i32 s93, s92, 15
	s_mov_b32 s94, s93
	s_mul_i32 s94, s94, 0x800
	s_add_i32 s94, s94, 0xd80000
	s_waitcnt lgkmcnt(0)
	v_cvt_pk_bf16_f32 v183, v179, v179
	v_add_u32_e32 v231, s94, v199
	global_store_short v231, v183, s[70:71]
	s_cmpk_gt_u32 s91, 0x7cf
	s_cbranch_scc1 .Lp0t_mx_done
; DI unsigned short f2bf(float x) { return (unsigned short)(pk2(x, 0.f) & 0xffffu); }
; DI void transpose_tile(unsigned char* smem, const int tid, const float* src, int K, int N, bf16_t* dst, int ldd, int permid, int kt, int nt) {
;     ...
;     for (int i = 0; i < 16; ++i) {
;         int kk = i * 4 + (tid >> 6), nn = tid & 63;
;         tv[i] = (n0 + nn < N) ? src[(size_t)(k0 + kk) * N + n0 + nn] : 0.f;
;     }
; #pragma unroll
;     for (int i = 0; i < 16; ++i) tile[tid & 63][i * 4 + (tid >> 6)] = tv[i];
;     __syncthreads();
; #pragma unroll 4
;     for (int i = 0; i < 16; ++i) {
;         int nn = i * 4 + (tid >> 6), kk = tid & 63;
;         int n = n0 + nn;
;         if (n < N) {
;             int row = n;
;             if (permid == 1) row = (n < 2048) ? n : ((n >= 2056) ? n - 8 : -1);
;             else if (permid == 2) row = (n < 1024) ? ((n >> 2) * 8 + (n & 3)) : (((n - 1024) >> 2) * 8 + 4 + (n & 3));
;             else if (permid == 3) row = (n < 2816) ? ((n >> 2) * 8 + (n & 3)) : (((n - 2816) >> 2) * 8 + 4 + (n & 3));
;             if (row >= 0) dst[(size_t)row * ldd + k0 + kk] = f2bf(tile[nn][kk]);
;         }
;     }
	s_waitcnt vmcnt(16)
	ds_write2_b32 v195, v200, v201 offset0:0 offset1:4
	ds_write2_b32 v195, v202, v203 offset0:8 offset1:12
	ds_write2_b32 v195, v204, v205 offset0:16 offset1:20
	ds_write2_b32 v195, v206, v207 offset0:24 offset1:28
	ds_write2_b32 v195, v208, v209 offset0:32 offset1:36
	ds_write2_b32 v195, v210, v211 offset0:40 offset1:44
	ds_write2_b32 v195, v212, v213 offset0:48 offset1:52
	ds_write2_b32 v195, v214, v215 offset0:56 offset1:60
	s_waitcnt lgkmcnt(0)
	ds_read_b32 v200, v187 offset:0
	ds_read_b32 v201, v187 offset:272
	ds_read_b32 v202, v187 offset:544
	ds_read_b32 v203, v187 offset:816
	ds_read_b32 v204, v187 offset:1088
	ds_read_b32 v205, v187 offset:1360
	ds_read_b32 v206, v187 offset:1632
	ds_read_b32 v207, v187 offset:1904
	ds_read_b32 v208, v187 offset:2176
	ds_read_b32 v209, v187 offset:2448
	ds_read_b32 v210, v187 offset:2720
	ds_read_b32 v211, v187 offset:2992
	ds_read_b32 v212, v187 offset:3264
	ds_read_b32 v213, v187 offset:3536
	ds_read_b32 v214, v187 offset:3808
	ds_read_b32 v215, v187 offset:4080
	s_add_i32 s93, s100, 0
	s_mov_b32 s94, s93
	s_mul_i32 s94, s94, 0x800
	s_add_i32 s94, s94, 0xd80000
	s_waitcnt lgkmcnt(15)
	v_cvt_pk_bf16_f32 v180, v200, v200
	v_add_u32_e32 v228, s94, v221
	global_store_short v228, v180, s[70:71]
	s_add_i32 s93, s100, 1
	s_mov_b32 s94, s93
	s_mul_i32 s94, s94, 0x800
	s_add_i32 s94, s94, 0xd80000
	s_waitcnt lgkmcnt(14)
	v_cvt_pk_bf16_f32 v181, v201, v201
	v_add_u32_e32 v229, s94, v221
	global_store_short v229, v181, s[70:71]
	s_add_i32 s93, s100, 2
	s_mov_b32 s94, s93
	s_mul_i32 s94, s94, 0x800
	s_add_i32 s94, s94, 0xd80000
	s_waitcnt lgkmcnt(13)
	v_cvt_pk_bf16_f32 v182, v202, v202
	v_add_u32_e32 v230, s94, v221
	global_store_short v230, v182, s[70:71]
	s_add_i32 s93, s100, 3
	s_mov_b32 s94, s93
	s_mul_i32 s94, s94, 0x800
	s_add_i32 s94, s94, 0xd80000
	s_waitcnt lgkmcnt(12)
	v_cvt_pk_bf16_f32 v183, v203, v203
	v_add_u32_e32 v231, s94, v221
	global_store_short v231, v183, s[70:71]
	s_add_i32 s93, s100, 4
	s_mov_b32 s94, s93
	s_mul_i32 s94, s94, 0x800
	s_add_i32 s94, s94, 0xd80000
	s_waitcnt lgkmcnt(11)
	v_cvt_pk_bf16_f32 v184, v204, v204
	v_add_u32_e32 v228, s94, v221
	global_store_short v228, v184, s[70:71]
	s_add_i32 s93, s100, 5
	s_mov_b32 s94, s93
	s_mul_i32 s94, s94, 0x800
	s_add_i32 s94, s94, 0xd80000
	s_waitcnt lgkmcnt(10)
	v_cvt_pk_bf16_f32 v185, v205, v205
	v_add_u32_e32 v229, s94, v221
	global_store_short v229, v185, s[70:71]
	s_add_i32 s93, s100, 6
	s_mov_b32 s94, s93
	s_mul_i32 s94, s94, 0x800
	s_add_i32 s94, s94, 0xd80000
	s_waitcnt lgkmcnt(9)
	v_cvt_pk_bf16_f32 v180, v206, v206
	v_add_u32_e32 v230, s94, v221
	global_store_short v230, v180, s[70:71]
	s_add_i32 s93, s100, 7
	s_mov_b32 s94, s93
	s_mul_i32 s94, s94, 0x800
	s_add_i32 s94, s94, 0xd80000
	s_waitcnt lgkmcnt(8)
	v_cvt_pk_bf16_f32 v181, v207, v207
	v_add_u32_e32 v231, s94, v221
	global_store_short v231, v181, s[70:71]
	s_add_i32 s93, s100, 8
	s_mov_b32 s94, s93
	s_mul_i32 s94, s94, 0x800
	s_add_i32 s94, s94, 0xd80000
	s_waitcnt lgkmcnt(7)
	v_cvt_pk_bf16_f32 v182, v208, v208
	v_add_u32_e32 v228, s94, v221
	global_store_short v228, v182, s[70:71]
	s_add_i32 s93, s100, 9
	s_mov_b32 s94, s93
	s_mul_i32 s94, s94, 0x800
	s_add_i32 s94, s94, 0xd80000
	s_waitcnt lgkmcnt(6)
	v_cvt_pk_bf16_f32 v183, v209, v209
	v_add_u32_e32 v229, s94, v221
	global_store_short v229, v183, s[70:71]
	s_add_i32 s93, s100, 10
	s_mov_b32 s94, s93
	s_mul_i32 s94, s94, 0x800
	s_add_i32 s94, s94, 0xd80000
	s_waitcnt lgkmcnt(5)
	v_cvt_pk_bf16_f32 v184, v210, v210
	v_add_u32_e32 v230, s94, v221
	global_store_short v230, v184, s[70:71]
	s_add_i32 s93, s100, 11
	s_mov_b32 s94, s93
	s_mul_i32 s94, s94, 0x800
	s_add_i32 s94, s94, 0xd80000
	s_waitcnt lgkmcnt(4)
	v_cvt_pk_bf16_f32 v185, v211, v211
	v_add_u32_e32 v231, s94, v221
	global_store_short v231, v185, s[70:71]
	s_add_i32 s93, s100, 12
	s_mov_b32 s94, s93
	s_mul_i32 s94, s94, 0x800
	s_add_i32 s94, s94, 0xd80000
	s_waitcnt lgkmcnt(3)
	v_cvt_pk_bf16_f32 v180, v212, v212
	v_add_u32_e32 v228, s94, v221
	global_store_short v228, v180, s[70:71]
	s_add_i32 s93, s100, 13
	s_mov_b32 s94, s93
	s_mul_i32 s94, s94, 0x800
	s_add_i32 s94, s94, 0xd80000
	s_waitcnt lgkmcnt(2)
	v_cvt_pk_bf16_f32 v181, v213, v213
	v_add_u32_e32 v229, s94, v221
	global_store_short v229, v181, s[70:71]
	s_add_i32 s93, s100, 14
	s_mov_b32 s94, s93
	s_mul_i32 s94, s94, 0x800
	s_add_i32 s94, s94, 0xd80000
	s_waitcnt lgkmcnt(1)
	v_cvt_pk_bf16_f32 v182, v214, v214
	v_add_u32_e32 v230, s94, v221
	global_store_short v230, v182, s[70:71]
	s_add_i32 s93, s100, 15
	s_mov_b32 s94, s93
	s_mul_i32 s94, s94, 0x800
	s_add_i32 s94, s94, 0xd80000
	s_waitcnt lgkmcnt(0)
	v_cvt_pk_bf16_f32 v183, v215, v215
	v_add_u32_e32 v231, s94, v221
	global_store_short v231, v183, s[70:71]
	v_add_u32_e32 v67, s90, v67
	v_add_u16_e32 v117, s90, v117
; DI void transpose_tile(unsigned char* smem, const int tid, const float* src, int K, int N, bf16_t* dst, int ldd, int permid, int kt, int nt) {
;     ...
;     for (int i = 0; i < 16; ++i) {
;         int kk = i * 4 + (tid >> 6), nn = tid & 63;
;         tv[i] = (n0 + nn < N) ? src[(size_t)(k0 + kk) * N + n0 + nn] : 0.f;
;     }
; #pragma unroll
;     for (int i = 0; i < 16; ++i) tile[tid & 63][i * 4 + (tid >> 6)] = tv[i];
; DI void phase0(const Params& p, unsigned char* smem, const int tid, const int vb, const int nvb) {
;     ...
;             if (id < 256) { transpose_tile(smem, tid, p.in[11], 1024, 1024, (bf16_t*)(ws + OFF_WDN), 1024, 0, id >> 4, id & 15); continue; }
;             id -= 256;
;             if (id < 256) { transpose_tile(smem, tid, p.in[20], 512, 2048, (bf16_t*)(ws + OFF_WGL), 512, 2, id >> 5, id & 31); continue; }
.Lp0t_mx_done:
.LBB0_65:
	s_or_b64 exec, exec, s[4:5]
.LBB0_66:
	s_andn2_saveexec_b64 s[4:5], s[30:31]
	s_cbranch_execz .LBB0_78
	v_lshrrev_b32_e32 v191, 4, v64
	v_and_b32_e32 v197, 15, v64
	s_mov_b64 s[88:89], 0x8000
	v_lshlrev_b32_e32 v196, 6, v191
	v_readfirstlane_b32 s91, v4
	v_add_u32_e32 v190, 0xfffffa30, v4
	v_and_b32_e32 v189, 31, v190
	v_lshrrev_b32_e32 v188, 5, v190
	v_lshlrev_b32_e32 v190, 6, v189
	v_lshlrev_b32_e32 v192, 6, v188
	v_lshl_add_u32 v198, v66, 4, v190
	v_add_u32_e32 v193, v192, v191
	v_mul_u32_u24_e32 v193, 0x800, v193
	v_add_lshl_u32 v193, v193, v198, 2
	v_sub_u32_e32 v193, v193, v196
	v_add_co_u32_e32 v194, vcc, v90, v193
	v_readfirstlane_b32 s92, v198
	v_add_lshl_u32 v199, v192, v64, 1
	v_addc_co_u32_e32 v195, vcc, 0, v91, vcc
	global_load_dword v164, v[194:195], off
	v_lshl_add_u64 v[194:195], v[194:195], 0, s[88:89]
	global_load_dword v165, v[194:195], off
	v_lshl_add_u64 v[194:195], v[194:195], 0, s[88:89]
	global_load_dword v166, v[194:195], off
	v_lshl_add_u64 v[194:195], v[194:195], 0, s[88:89]
	global_load_dword v167, v[194:195], off
	v_lshl_add_u64 v[194:195], v[194:195], 0, s[88:89]
	global_load_dword v168, v[194:195], off
	v_lshl_add_u64 v[194:195], v[194:195], 0, s[88:89]
	global_load_dword v169, v[194:195], off
	v_lshl_add_u64 v[194:195], v[194:195], 0, s[88:89]
	global_load_dword v170, v[194:195], off
	v_lshl_add_u64 v[194:195], v[194:195], 0, s[88:89]
	global_load_dword v171, v[194:195], off
	v_lshl_add_u64 v[194:195], v[194:195], 0, s[88:89]
	global_load_dword v172, v[194:195], off
	v_lshl_add_u64 v[194:195], v[194:195], 0, s[88:89]
	global_load_dword v173, v[194:195], off
	v_lshl_add_u64 v[194:195], v[194:195], 0, s[88:89]
	global_load_dword v174, v[194:195], off
	v_lshl_add_u64 v[194:195], v[194:195], 0, s[88:89]
	global_load_dword v175, v[194:195], off
	v_lshl_add_u64 v[194:195], v[194:195], 0, s[88:89]
	global_load_dword v176, v[194:195], off
	v_lshl_add_u64 v[194:195], v[194:195], 0, s[88:89]
	global_load_dword v177, v[194:195], off
	v_lshl_add_u64 v[194:195], v[194:195], 0, s[88:89]
	global_load_dword v178, v[194:195], off
	v_lshl_add_u64 v[194:195], v[194:195], 0, s[88:89]
	global_load_dword v179, v[194:195], off
	s_add_i32 s91, s91, 0x200
	s_mov_b32 s98, 0
	s_cmpk_gt_u32 s91, 0x6cf
	s_cbranch_scc1 .Lp0t_gl_l1
	v_add_u32_e32 v224, 0xfffffc30, v4
	v_and_b32_e32 v223, 31, v224
	v_lshrrev_b32_e32 v222, 5, v224
	v_lshlrev_b32_e32 v224, 6, v223
	v_lshlrev_b32_e32 v220, 6, v222
	v_lshl_add_u32 v226, v66, 4, v224
	v_add_u32_e32 v225, v220, v191
	v_mul_u32_u24_e32 v225, 0x800, v225
	v_add_lshl_u32 v225, v225, v226, 2
	v_sub_u32_e32 v225, v225, v196
	v_add_co_u32_e32 v216, vcc, v90, v225
	v_readfirstlane_b32 s100, v226
	v_add_lshl_u32 v221, v220, v64, 1
	v_addc_co_u32_e32 v217, vcc, 0, v91, vcc
	global_load_dword v200, v[216:217], off
	v_lshl_add_u64 v[216:217], v[216:217], 0, s[88:89]
	global_load_dword v201, v[216:217], off
	v_lshl_add_u64 v[216:217], v[216:217], 0, s[88:89]
	global_load_dword v202, v[216:217], off
	v_lshl_add_u64 v[216:217], v[216:217], 0, s[88:89]
	global_load_dword v203, v[216:217], off
	v_lshl_add_u64 v[216:217], v[216:217], 0, s[88:89]
	global_load_dword v204, v[216:217], off
	v_lshl_add_u64 v[216:217], v[216:217], 0, s[88:89]
	global_load_dword v205, v[216:217], off
	v_lshl_add_u64 v[216:217], v[216:217], 0, s[88:89]
	global_load_dword v206, v[216:217], off
	v_lshl_add_u64 v[216:217], v[216:217], 0, s[88:89]
	global_load_dword v207, v[216:217], off
	v_lshl_add_u64 v[216:217], v[216:217], 0, s[88:89]
	global_load_dword v208, v[216:217], off
	v_lshl_add_u64 v[216:217], v[216:217], 0, s[88:89]
	global_load_dword v209, v[216:217], off
	v_lshl_add_u64 v[216:217], v[216:217], 0, s[88:89]
	global_load_dword v210, v[216:217], off
	v_lshl_add_u64 v[216:217], v[216:217], 0, s[88:89]
	global_load_dword v211, v[216:217], off
	v_lshl_add_u64 v[216:217], v[216:217], 0, s[88:89]
	global_load_dword v212, v[216:217], off
	v_lshl_add_u64 v[216:217], v[216:217], 0, s[88:89]
	global_load_dword v213, v[216:217], off
	v_lshl_add_u64 v[216:217], v[216:217], 0, s[88:89]
	global_load_dword v214, v[216:217], off
	v_lshl_add_u64 v[216:217], v[216:217], 0, s[88:89]
	global_load_dword v215, v[216:217], off
.Lp0t_gl_l1:
	v_lshrrev_b32_e32 v186, 8, v250
	v_mul_u32_u24_e32 v195, 0x1100, v66
	v_lshlrev_b32_e32 v186, 16, v186
	v_mul_u32_u24_e32 v187, 0x110, v197
	v_add_u32_e32 v186, v186, v195
	v_lshl_add_u32 v195, v191, 2, v187
	v_add_u32_e32 v186, 0x8010, v186
	v_lshl_add_u32 v187, v64, 2, v186
	v_add_u32_e32 v195, v195, v186
	s_cmpk_gt_u32 s91, 0x6cf
	s_cbranch_scc1 .Lp0t_gl_w1
	s_waitcnt vmcnt(16)
	s_branch .Lp0t_gl_w2

; DI unsigned short f2bf(float x) { return (unsigned short)(pk2(x, 0.f) & 0xffffu); }
; DI void transpose_tile(unsigned char* smem, const int tid, const float* src, int K, int N, bf16_t* dst, int ldd, int permid, int kt, int nt) {
;     ...
;     for (int i = 0; i < 16; ++i) tile[tid & 63][i * 4 + (tid >> 6)] = tv[i];
;     __syncthreads();
; #pragma unroll 4
;     for (int i = 0; i < 16; ++i) {
;         int nn = i * 4 + (tid >> 6), kk = tid & 63;
;         int n = n0 + nn;
;         if (n < N) {
;             int row = n;
;             if (permid == 1) row = (n < 2048) ? n : ((n >= 2056) ? n - 8 : -1);
;             else if (permid == 2) row = (n < 1024) ? ((n >> 2) * 8 + (n & 3)) : (((n - 1024) >> 2) * 8 + 4 + (n & 3));
;             else if (permid == 3) row = (n < 2816) ? ((n >> 2) * 8 + (n & 3)) : (((n - 2816) >> 2) * 8 + 4 + (n & 3));
;             if (row >= 0) dst[(size_t)row * ldd + k0 + kk] = f2bf(tile[nn][kk]);
;         }
;     }
.Lp0t_gl_w2:
	ds_write2_b32 v195, v164, v165 offset0:0 offset1:4
	ds_write2_b32 v195, v166, v167 offset0:8 offset1:12
	ds_write2_b32 v195, v168, v169 offset0:16 offset1:20
	ds_write2_b32 v195, v170, v171 offset0:24 offset1:28
	ds_write2_b32 v195, v172, v173 offset0:32 offset1:36
	ds_write2_b32 v195, v174, v175 offset0:40 offset1:44
	ds_write2_b32 v195, v176, v177 offset0:48 offset1:52
	ds_write2_b32 v195, v178, v179 offset0:56 offset1:60
	s_waitcnt lgkmcnt(0)
	ds_read_b32 v164, v187 offset:0
	ds_read_b32 v165, v187 offset:272
	ds_read_b32 v166, v187 offset:544
	ds_read_b32 v167, v187 offset:816
	ds_read_b32 v168, v187 offset:1088
	ds_read_b32 v169, v187 offset:1360
	ds_read_b32 v170, v187 offset:1632
	ds_read_b32 v171, v187 offset:1904
	ds_read_b32 v172, v187 offset:2176
	ds_read_b32 v173, v187 offset:2448
	ds_read_b32 v174, v187 offset:2720
	ds_read_b32 v175, v187 offset:2992
	ds_read_b32 v176, v187 offset:3264
	ds_read_b32 v177, v187 offset:3536
	ds_read_b32 v178, v187 offset:3808
	ds_read_b32 v179, v187 offset:4080
	s_add_i32 s93, s92, 0
	s_cmpk_lt_u32 s93, 0x400
	s_cselect_b32 s95, 0, 0x400
	s_cselect_b32 s94, 0, 4
	s_sub_i32 s95, s93, s95
	s_lshr_b32 s93, s95, 2
	s_and_b32 s95, s95, 3
	s_lshl_b32 s93, s93, 3
	s_add_i32 s94, s94, s95
	s_add_i32 s94, s94, s93
	s_mul_i32 s94, s94, 0x400
	s_add_i32 s94, s94, 0xb80000
	s_waitcnt lgkmcnt(15)
	v_cvt_pk_bf16_f32 v180, v164, v164
	v_add_u32_e32 v228, s94, v199
	global_store_short v228, v180, s[70:71]
	s_add_i32 s93, s92, 1
	s_cmpk_lt_u32 s93, 0x400
	s_cselect_b32 s95, 0, 0x400
	s_cselect_b32 s94, 0, 4
	s_sub_i32 s95, s93, s95
	s_lshr_b32 s93, s95, 2
	s_and_b32 s95, s95, 3
	s_lshl_b32 s93, s93, 3
	s_add_i32 s94, s94, s95
	s_add_i32 s94, s94, s93
	s_mul_i32 s94, s94, 0x400
	s_add_i32 s94, s94, 0xb80000
	s_waitcnt lgkmcnt(14)
	v_cvt_pk_bf16_f32 v181, v165, v165
	v_add_u32_e32 v229, s94, v199
	global_store_short v229, v181, s[70:71]
	s_add_i32 s93, s92, 2
	s_cmpk_lt_u32 s93, 0x400
	s_cselect_b32 s95, 0, 0x400
	s_cselect_b32 s94, 0, 4
	s_sub_i32 s95, s93, s95
	s_lshr_b32 s93, s95, 2
	s_and_b32 s95, s95, 3
	s_lshl_b32 s93, s93, 3
	s_add_i32 s94, s94, s95
	s_add_i32 s94, s94, s93
	s_mul_i32 s94, s94, 0x400
	s_add_i32 s94, s94, 0xb80000
	s_waitcnt lgkmcnt(13)
	v_cvt_pk_bf16_f32 v182, v166, v166
	v_add_u32_e32 v230, s94, v199
	global_store_short v230, v182, s[70:71]
	s_add_i32 s93, s92, 3
	s_cmpk_lt_u32 s93, 0x400
	s_cselect_b32 s95, 0, 0x400
	s_cselect_b32 s94, 0, 4
	s_sub_i32 s95, s93, s95
	s_lshr_b32 s93, s95, 2
	s_and_b32 s95, s95, 3
	s_lshl_b32 s93, s93, 3
	s_add_i32 s94, s94, s95
	s_add_i32 s94, s94, s93
	s_mul_i32 s94, s94, 0x400
	s_add_i32 s94, s94, 0xb80000
	s_waitcnt lgkmcnt(12)
	v_cvt_pk_bf16_f32 v183, v167, v167
	v_add_u32_e32 v231, s94, v199
	global_store_short v231, v183, s[70:71]
	s_add_i32 s93, s92, 4
	s_cmpk_lt_u32 s93, 0x400
	s_cselect_b32 s95, 0, 0x400
	s_cselect_b32 s94, 0, 4
	s_sub_i32 s95, s93, s95
	s_lshr_b32 s93, s95, 2
	s_and_b32 s95, s95, 3
	s_lshl_b32 s93, s93, 3
	s_add_i32 s94, s94, s95
	s_add_i32 s94, s94, s93
	s_mul_i32 s94, s94, 0x400
	s_add_i32 s94, s94, 0xb80000
	s_waitcnt lgkmcnt(11)
	v_cvt_pk_bf16_f32 v184, v168, v168
	v_add_u32_e32 v228, s94, v199
	global_store_short v228, v184, s[70:71]
	s_add_i32 s93, s92, 5
	s_cmpk_lt_u32 s93, 0x400
	s_cselect_b32 s95, 0, 0x400
	s_cselect_b32 s94, 0, 4
	s_sub_i32 s95, s93, s95
	s_lshr_b32 s93, s95, 2
	s_and_b32 s95, s95, 3
	s_lshl_b32 s93, s93, 3
	s_add_i32 s94, s94, s95
	s_add_i32 s94, s94, s93
	s_mul_i32 s94, s94, 0x400
	s_add_i32 s94, s94, 0xb80000
	s_waitcnt lgkmcnt(10)
	v_cvt_pk_bf16_f32 v185, v169, v169
	v_add_u32_e32 v229, s94, v199
	global_store_short v229, v185, s[70:71]
	s_add_i32 s93, s92, 6
	s_cmpk_lt_u32 s93, 0x400
	s_cselect_b32 s95, 0, 0x400
	s_cselect_b32 s94, 0, 4
	s_sub_i32 s95, s93, s95
	s_lshr_b32 s93, s95, 2
	s_and_b32 s95, s95, 3
	s_lshl_b32 s93, s93, 3
	s_add_i32 s94, s94, s95
	s_add_i32 s94, s94, s93
	s_mul_i32 s94, s94, 0x400
	s_add_i32 s94, s94, 0xb80000
	s_waitcnt lgkmcnt(9)
	v_cvt_pk_bf16_f32 v180, v170, v170
	v_add_u32_e32 v230, s94, v199
	global_store_short v230, v180, s[70:71]
	s_add_i32 s93, s92, 7
	s_cmpk_lt_u32 s93, 0x400
	s_cselect_b32 s95, 0, 0x400
	s_cselect_b32 s94, 0, 4
	s_sub_i32 s95, s93, s95
	s_lshr_b32 s93, s95, 2
	s_and_b32 s95, s95, 3
	s_lshl_b32 s93, s93, 3
	s_add_i32 s94, s94, s95
	s_add_i32 s94, s94, s93
	s_mul_i32 s94, s94, 0x400
	s_add_i32 s94, s94, 0xb80000
	s_waitcnt lgkmcnt(8)
	v_cvt_pk_bf16_f32 v181, v171, v171
	v_add_u32_e32 v231, s94, v199
	global_store_short v231, v181, s[70:71]
	s_add_i32 s93, s92, 8
	s_cmpk_lt_u32 s93, 0x400
	s_cselect_b32 s95, 0, 0x400
	s_cselect_b32 s94, 0, 4
	s_sub_i32 s95, s93, s95
	s_lshr_b32 s93, s95, 2
	s_and_b32 s95, s95, 3
	s_lshl_b32 s93, s93, 3
	s_add_i32 s94, s94, s95
	s_add_i32 s94, s94, s93
	s_mul_i32 s94, s94, 0x400
	s_add_i32 s94, s94, 0xb80000
	s_waitcnt lgkmcnt(7)
	v_cvt_pk_bf16_f32 v182, v172, v172
	v_add_u32_e32 v228, s94, v199
	global_store_short v228, v182, s[70:71]
	s_add_i32 s93, s92, 9
	s_cmpk_lt_u32 s93, 0x400
	s_cselect_b32 s95, 0, 0x400
	s_cselect_b32 s94, 0, 4
	s_sub_i32 s95, s93, s95
	s_lshr_b32 s93, s95, 2
	s_and_b32 s95, s95, 3
	s_lshl_b32 s93, s93, 3
	s_add_i32 s94, s94, s95
	s_add_i32 s94, s94, s93
	s_mul_i32 s94, s94, 0x400
	s_add_i32 s94, s94, 0xb80000
	s_waitcnt lgkmcnt(6)
	v_cvt_pk_bf16_f32 v183, v173, v173
	v_add_u32_e32 v229, s94, v199
	global_store_short v229, v183, s[70:71]
	s_add_i32 s93, s92, 10
	s_cmpk_lt_u32 s93, 0x400
	s_cselect_b32 s95, 0, 0x400
	s_cselect_b32 s94, 0, 4
	s_sub_i32 s95, s93, s95
	s_lshr_b32 s93, s95, 2
	s_and_b32 s95, s95, 3
	s_lshl_b32 s93, s93, 3
	s_add_i32 s94, s94, s95
	s_add_i32 s94, s94, s93
	s_mul_i32 s94, s94, 0x400
	s_add_i32 s94, s94, 0xb80000
	s_waitcnt lgkmcnt(5)
; DI unsigned short f2bf(float x) { return (unsigned short)(pk2(x, 0.f) & 0xffffu); }
; DI void transpose_tile(unsigned char* smem, const int tid, const float* src, int K, int N, bf16_t* dst, int ldd, int permid, int kt, int nt) {
;     ...
;     for (int i = 0; i < 16; ++i) tile[tid & 63][i * 4 + (tid >> 6)] = tv[i];
;     __syncthreads();
; #pragma unroll 4
;     for (int i = 0; i < 16; ++i) {
;         int nn = i * 4 + (tid >> 6), kk = tid & 63;
;         int n = n0 + nn;
;         if (n < N) {
;             int row = n;
;             if (permid == 1) row = (n < 2048) ? n : ((n >= 2056) ? n - 8 : -1);
;             else if (permid == 2) row = (n < 1024) ? ((n >> 2) * 8 + (n & 3)) : (((n - 1024) >> 2) * 8 + 4 + (n & 3));
;             else if (permid == 3) row = (n < 2816) ? ((n >> 2) * 8 + (n & 3)) : (((n - 2816) >> 2) * 8 + 4 + (n & 3));
;             if (row >= 0) dst[(size_t)row * ldd + k0 + kk] = f2bf(tile[nn][kk]);
;         }
;     }
	v_cvt_pk_bf16_f32 v184, v174, v174
	v_add_u32_e32 v230, s94, v199
	global_store_short v230, v184, s[70:71]
	s_add_i32 s93, s92, 11
	s_cmpk_lt_u32 s93, 0x400
	s_cselect_b32 s95, 0, 0x400
	s_cselect_b32 s94, 0, 4
	s_sub_i32 s95, s93, s95
	s_lshr_b32 s93, s95, 2
	s_and_b32 s95, s95, 3
	s_lshl_b32 s93, s93, 3
	s_add_i32 s94, s94, s95
	s_add_i32 s94, s94, s93
	s_mul_i32 s94, s94, 0x400
	s_add_i32 s94, s94, 0xb80000
	s_waitcnt lgkmcnt(4)
	v_cvt_pk_bf16_f32 v185, v175, v175
	v_add_u32_e32 v231, s94, v199
	global_store_short v231, v185, s[70:71]
	s_add_i32 s93, s92, 12
	s_cmpk_lt_u32 s93, 0x400
	s_cselect_b32 s95, 0, 0x400
	s_cselect_b32 s94, 0, 4
	s_sub_i32 s95, s93, s95
	s_lshr_b32 s93, s95, 2
	s_and_b32 s95, s95, 3
	s_lshl_b32 s93, s93, 3
	s_add_i32 s94, s94, s95
	s_add_i32 s94, s94, s93
	s_mul_i32 s94, s94, 0x400
	s_add_i32 s94, s94, 0xb80000
	s_waitcnt lgkmcnt(3)
	v_cvt_pk_bf16_f32 v180, v176, v176
	v_add_u32_e32 v228, s94, v199
	global_store_short v228, v180, s[70:71]
	s_add_i32 s93, s92, 13
	s_cmpk_lt_u32 s93, 0x400
	s_cselect_b32 s95, 0, 0x400
	s_cselect_b32 s94, 0, 4
	s_sub_i32 s95, s93, s95
	s_lshr_b32 s93, s95, 2
	s_and_b32 s95, s95, 3
	s_lshl_b32 s93, s93, 3
	s_add_i32 s94, s94, s95
	s_add_i32 s94, s94, s93
	s_mul_i32 s94, s94, 0x400
	s_add_i32 s94, s94, 0xb80000
	s_waitcnt lgkmcnt(2)
	v_cvt_pk_bf16_f32 v181, v177, v177
	v_add_u32_e32 v229, s94, v199
	global_store_short v229, v181, s[70:71]
	s_add_i32 s93, s92, 14
	s_cmpk_lt_u32 s93, 0x400
	s_cselect_b32 s95, 0, 0x400
	s_cselect_b32 s94, 0, 4
	s_sub_i32 s95, s93, s95
	s_lshr_b32 s93, s95, 2
	s_and_b32 s95, s95, 3
	s_lshl_b32 s93, s93, 3
	s_add_i32 s94, s94, s95
	s_add_i32 s94, s94, s93
	s_mul_i32 s94, s94, 0x400
	s_add_i32 s94, s94, 0xb80000
	s_waitcnt lgkmcnt(1)
	v_cvt_pk_bf16_f32 v182, v178, v178
	v_add_u32_e32 v230, s94, v199
	global_store_short v230, v182, s[70:71]
	s_add_i32 s93, s92, 15
	s_cmpk_lt_u32 s93, 0x400
	s_cselect_b32 s95, 0, 0x400
	s_cselect_b32 s94, 0, 4
	s_sub_i32 s95, s93, s95
	s_lshr_b32 s93, s95, 2
	s_and_b32 s95, s95, 3
	s_lshl_b32 s93, s93, 3
	s_add_i32 s94, s94, s95
	s_add_i32 s94, s94, s93
	s_mul_i32 s94, s94, 0x400
	s_add_i32 s94, s94, 0xb80000
	s_waitcnt lgkmcnt(0)
	v_cvt_pk_bf16_f32 v183, v179, v179
	v_add_u32_e32 v231, s94, v199
	global_store_short v231, v183, s[70:71]
	s_cmpk_gt_u32 s91, 0x6cf
	s_cbranch_scc1 .Lp0t_gl_done
	s_waitcnt vmcnt(16)
	ds_write2_b32 v195, v200, v201 offset0:0 offset1:4
	ds_write2_b32 v195, v202, v203 offset0:8 offset1:12
	ds_write2_b32 v195, v204, v205 offset0:16 offset1:20
	ds_write2_b32 v195, v206, v207 offset0:24 offset1:28
	ds_write2_b32 v195, v208, v209 offset0:32 offset1:36
	ds_write2_b32 v195, v210, v211 offset0:40 offset1:44
	ds_write2_b32 v195, v212, v213 offset0:48 offset1:52
	ds_write2_b32 v195, v214, v215 offset0:56 offset1:60
	s_waitcnt lgkmcnt(0)
	ds_read_b32 v200, v187 offset:0
	ds_read_b32 v201, v187 offset:272
	ds_read_b32 v202, v187 offset:544
	ds_read_b32 v203, v187 offset:816
	ds_read_b32 v204, v187 offset:1088
	ds_read_b32 v205, v187 offset:1360
	ds_read_b32 v206, v187 offset:1632
	ds_read_b32 v207, v187 offset:1904
	ds_read_b32 v208, v187 offset:2176
	ds_read_b32 v209, v187 offset:2448
	ds_read_b32 v210, v187 offset:2720
	ds_read_b32 v211, v187 offset:2992
	ds_read_b32 v212, v187 offset:3264
	ds_read_b32 v213, v187 offset:3536
	ds_read_b32 v214, v187 offset:3808
	ds_read_b32 v215, v187 offset:4080
	s_add_i32 s93, s100, 0
	s_cmpk_lt_u32 s93, 0x400
	s_cselect_b32 s95, 0, 0x400
	s_cselect_b32 s94, 0, 4
	s_sub_i32 s95, s93, s95
	s_lshr_b32 s93, s95, 2
	s_and_b32 s95, s95, 3
	s_lshl_b32 s93, s93, 3
	s_add_i32 s94, s94, s95
	s_add_i32 s94, s94, s93
	s_mul_i32 s94, s94, 0x400
	s_add_i32 s94, s94, 0xb80000
	s_waitcnt lgkmcnt(15)
	v_cvt_pk_bf16_f32 v180, v200, v200
	v_add_u32_e32 v228, s94, v221
	global_store_short v228, v180, s[70:71]
	s_add_i32 s93, s100, 1
	s_cmpk_lt_u32 s93, 0x400
	s_cselect_b32 s95, 0, 0x400
	s_cselect_b32 s94, 0, 4
	s_sub_i32 s95, s93, s95
	s_lshr_b32 s93, s95, 2
	s_and_b32 s95, s95, 3
	s_lshl_b32 s93, s93, 3
	s_add_i32 s94, s94, s95
	s_add_i32 s94, s94, s93
	s_mul_i32 s94, s94, 0x400
	s_add_i32 s94, s94, 0xb80000
	s_waitcnt lgkmcnt(14)
	v_cvt_pk_bf16_f32 v181, v201, v201
	v_add_u32_e32 v229, s94, v221
	global_store_short v229, v181, s[70:71]
	s_add_i32 s93, s100, 2
	s_cmpk_lt_u32 s93, 0x400
	s_cselect_b32 s95, 0, 0x400
	s_cselect_b32 s94, 0, 4
	s_sub_i32 s95, s93, s95
	s_lshr_b32 s93, s95, 2
	s_and_b32 s95, s95, 3
	s_lshl_b32 s93, s93, 3
	s_add_i32 s94, s94, s95
	s_add_i32 s94, s94, s93
	s_mul_i32 s94, s94, 0x400
	s_add_i32 s94, s94, 0xb80000
	s_waitcnt lgkmcnt(13)
	v_cvt_pk_bf16_f32 v182, v202, v202
	v_add_u32_e32 v230, s94, v221
	global_store_short v230, v182, s[70:71]
	s_add_i32 s93, s100, 3
	s_cmpk_lt_u32 s93, 0x400
	s_cselect_b32 s95, 0, 0x400
	s_cselect_b32 s94, 0, 4
	s_sub_i32 s95, s93, s95
	s_lshr_b32 s93, s95, 2
	s_and_b32 s95, s95, 3
	s_lshl_b32 s93, s93, 3
	s_add_i32 s94, s94, s95
	s_add_i32 s94, s94, s93
	s_mul_i32 s94, s94, 0x400
	s_add_i32 s94, s94, 0xb80000
	s_waitcnt lgkmcnt(12)
; DI unsigned short f2bf(float x) { return (unsigned short)(pk2(x, 0.f) & 0xffffu); }
; DI void transpose_tile(unsigned char* smem, const int tid, const float* src, int K, int N, bf16_t* dst, int ldd, int permid, int kt, int nt) {
;     ...
;     for (int i = 0; i < 16; ++i) tile[tid & 63][i * 4 + (tid >> 6)] = tv[i];
;     __syncthreads();
; #pragma unroll 4
;     for (int i = 0; i < 16; ++i) {
;         int nn = i * 4 + (tid >> 6), kk = tid & 63;
;         int n = n0 + nn;
;         if (n < N) {
;             int row = n;
;             if (permid == 1) row = (n < 2048) ? n : ((n >= 2056) ? n - 8 : -1);
;             else if (permid == 2) row = (n < 1024) ? ((n >> 2) * 8 + (n & 3)) : (((n - 1024) >> 2) * 8 + 4 + (n & 3));
;             else if (permid == 3) row = (n < 2816) ? ((n >> 2) * 8 + (n & 3)) : (((n - 2816) >> 2) * 8 + 4 + (n & 3));
;             if (row >= 0) dst[(size_t)row * ldd + k0 + kk] = f2bf(tile[nn][kk]);
;         }
;     }
	v_cvt_pk_bf16_f32 v183, v203, v203
	v_add_u32_e32 v231, s94, v221
	global_store_short v231, v183, s[70:71]
	s_add_i32 s93, s100, 4
	s_cmpk_lt_u32 s93, 0x400
	s_cselect_b32 s95, 0, 0x400
	s_cselect_b32 s94, 0, 4
	s_sub_i32 s95, s93, s95
	s_lshr_b32 s93, s95, 2
	s_and_b32 s95, s95, 3
	s_lshl_b32 s93, s93, 3
	s_add_i32 s94, s94, s95
	s_add_i32 s94, s94, s93
	s_mul_i32 s94, s94, 0x400
	s_add_i32 s94, s94, 0xb80000
	s_waitcnt lgkmcnt(11)
	v_cvt_pk_bf16_f32 v184, v204, v204
	v_add_u32_e32 v228, s94, v221
	global_store_short v228, v184, s[70:71]
	s_add_i32 s93, s100, 5
	s_cmpk_lt_u32 s93, 0x400
	s_cselect_b32 s95, 0, 0x400
	s_cselect_b32 s94, 0, 4
	s_sub_i32 s95, s93, s95
	s_lshr_b32 s93, s95, 2
	s_and_b32 s95, s95, 3
	s_lshl_b32 s93, s93, 3
	s_add_i32 s94, s94, s95
	s_add_i32 s94, s94, s93
	s_mul_i32 s94, s94, 0x400
	s_add_i32 s94, s94, 0xb80000
	s_waitcnt lgkmcnt(10)
	v_cvt_pk_bf16_f32 v185, v205, v205
	v_add_u32_e32 v229, s94, v221
	global_store_short v229, v185, s[70:71]
	s_add_i32 s93, s100, 6
	s_cmpk_lt_u32 s93, 0x400
	s_cselect_b32 s95, 0, 0x400
	s_cselect_b32 s94, 0, 4
	s_sub_i32 s95, s93, s95
	s_lshr_b32 s93, s95, 2
	s_and_b32 s95, s95, 3
	s_lshl_b32 s93, s93, 3
	s_add_i32 s94, s94, s95
	s_add_i32 s94, s94, s93
	s_mul_i32 s94, s94, 0x400
	s_add_i32 s94, s94, 0xb80000
	s_waitcnt lgkmcnt(9)
	v_cvt_pk_bf16_f32 v180, v206, v206
	v_add_u32_e32 v230, s94, v221
	global_store_short v230, v180, s[70:71]
	s_add_i32 s93, s100, 7
	s_cmpk_lt_u32 s93, 0x400
	s_cselect_b32 s95, 0, 0x400
	s_cselect_b32 s94, 0, 4
	s_sub_i32 s95, s93, s95
	s_lshr_b32 s93, s95, 2
	s_and_b32 s95, s95, 3
	s_lshl_b32 s93, s93, 3
	s_add_i32 s94, s94, s95
	s_add_i32 s94, s94, s93
	s_mul_i32 s94, s94, 0x400
	s_add_i32 s94, s94, 0xb80000
	s_waitcnt lgkmcnt(8)
	v_cvt_pk_bf16_f32 v181, v207, v207
	v_add_u32_e32 v231, s94, v221
	global_store_short v231, v181, s[70:71]
	s_add_i32 s93, s100, 8
	s_cmpk_lt_u32 s93, 0x400
	s_cselect_b32 s95, 0, 0x400
	s_cselect_b32 s94, 0, 4
	s_sub_i32 s95, s93, s95
	s_lshr_b32 s93, s95, 2
	s_and_b32 s95, s95, 3
	s_lshl_b32 s93, s93, 3
	s_add_i32 s94, s94, s95
	s_add_i32 s94, s94, s93
	s_mul_i32 s94, s94, 0x400
	s_add_i32 s94, s94, 0xb80000
	s_waitcnt lgkmcnt(7)
	v_cvt_pk_bf16_f32 v182, v208, v208
	v_add_u32_e32 v228, s94, v221
	global_store_short v228, v182, s[70:71]
	s_add_i32 s93, s100, 9
	s_cmpk_lt_u32 s93, 0x400
	s_cselect_b32 s95, 0, 0x400
	s_cselect_b32 s94, 0, 4
	s_sub_i32 s95, s93, s95
	s_lshr_b32 s93, s95, 2
	s_and_b32 s95, s95, 3
	s_lshl_b32 s93, s93, 3
	s_add_i32 s94, s94, s95
	s_add_i32 s94, s94, s93
	s_mul_i32 s94, s94, 0x400
	s_add_i32 s94, s94, 0xb80000
	s_waitcnt lgkmcnt(6)
	v_cvt_pk_bf16_f32 v183, v209, v209
	v_add_u32_e32 v229, s94, v221
	global_store_short v229, v183, s[70:71]
	s_add_i32 s93, s100, 10
	s_cmpk_lt_u32 s93, 0x400
	s_cselect_b32 s95, 0, 0x400
	s_cselect_b32 s94, 0, 4
	s_sub_i32 s95, s93, s95
	s_lshr_b32 s93, s95, 2
	s_and_b32 s95, s95, 3
	s_lshl_b32 s93, s93, 3
	s_add_i32 s94, s94, s95
	s_add_i32 s94, s94, s93
	s_mul_i32 s94, s94, 0x400
	s_add_i32 s94, s94, 0xb80000
	s_waitcnt lgkmcnt(5)
	v_cvt_pk_bf16_f32 v184, v210, v210
	v_add_u32_e32 v230, s94, v221
	global_store_short v230, v184, s[70:71]
	s_add_i32 s93, s100, 11
	s_cmpk_lt_u32 s93, 0x400
	s_cselect_b32 s95, 0, 0x400
	s_cselect_b32 s94, 0, 4
	s_sub_i32 s95, s93, s95
	s_lshr_b32 s93, s95, 2
	s_and_b32 s95, s95, 3
	s_lshl_b32 s93, s93, 3
	s_add_i32 s94, s94, s95
	s_add_i32 s94, s94, s93
	s_mul_i32 s94, s94, 0x400
	s_add_i32 s94, s94, 0xb80000
	s_waitcnt lgkmcnt(4)
	v_cvt_pk_bf16_f32 v185, v211, v211
	v_add_u32_e32 v231, s94, v221
	global_store_short v231, v185, s[70:71]
	s_add_i32 s93, s100, 12
	s_cmpk_lt_u32 s93, 0x400
	s_cselect_b32 s95, 0, 0x400
	s_cselect_b32 s94, 0, 4
	s_sub_i32 s95, s93, s95
	s_lshr_b32 s93, s95, 2
	s_and_b32 s95, s95, 3
	s_lshl_b32 s93, s93, 3
	s_add_i32 s94, s94, s95
	s_add_i32 s94, s94, s93
	s_mul_i32 s94, s94, 0x400
	s_add_i32 s94, s94, 0xb80000
	s_waitcnt lgkmcnt(3)
	v_cvt_pk_bf16_f32 v180, v212, v212
	v_add_u32_e32 v228, s94, v221
	global_store_short v228, v180, s[70:71]
	s_add_i32 s93, s100, 13
	s_cmpk_lt_u32 s93, 0x400
	s_cselect_b32 s95, 0, 0x400
	s_cselect_b32 s94, 0, 4
	s_sub_i32 s95, s93, s95
	s_lshr_b32 s93, s95, 2
	s_and_b32 s95, s95, 3
	s_lshl_b32 s93, s93, 3
	s_add_i32 s94, s94, s95
	s_add_i32 s94, s94, s93
	s_mul_i32 s94, s94, 0x400
	s_add_i32 s94, s94, 0xb80000
	s_waitcnt lgkmcnt(2)
	v_cvt_pk_bf16_f32 v181, v213, v213
	v_add_u32_e32 v229, s94, v221
	global_store_short v229, v181, s[70:71]
	s_add_i32 s93, s100, 14
	s_cmpk_lt_u32 s93, 0x400
	s_cselect_b32 s95, 0, 0x400
	s_cselect_b32 s94, 0, 4
	s_sub_i32 s95, s93, s95
	s_lshr_b32 s93, s95, 2
	s_and_b32 s95, s95, 3
	s_lshl_b32 s93, s93, 3
	s_add_i32 s94, s94, s95
	s_add_i32 s94, s94, s93
	s_mul_i32 s94, s94, 0x400
	s_add_i32 s94, s94, 0xb80000
	s_waitcnt lgkmcnt(1)
	v_cvt_pk_bf16_f32 v182, v214, v214
	v_add_u32_e32 v230, s94, v221
	global_store_short v230, v182, s[70:71]
	s_add_i32 s93, s100, 15
	s_cmpk_lt_u32 s93, 0x400
	s_cselect_b32 s95, 0, 0x400
	s_cselect_b32 s94, 0, 4
	s_sub_i32 s95, s93, s95
	s_lshr_b32 s93, s95, 2
	s_and_b32 s95, s95, 3
	s_lshl_b32 s93, s93, 3
	s_add_i32 s94, s94, s95
	s_add_i32 s94, s94, s93
	s_mul_i32 s94, s94, 0x400
	s_add_i32 s94, s94, 0xb80000
	s_waitcnt lgkmcnt(0)
	v_cvt_pk_bf16_f32 v183, v215, v215
	v_add_u32_e32 v231, s94, v221
	global_store_short v231, v183, s[70:71]
	v_add_u32_e32 v67, s90, v67
	v_add_u16_e32 v117, s90, v117

; DI void transpose_tile(unsigned char* smem, const int tid, const float* src, int K, int N, bf16_t* dst, int ldd, int permid, int kt, int nt) {
;     ...
;     for (int i = 0; i < 16; ++i) {
;         int kk = i * 4 + (tid >> 6), nn = tid & 63;
;         tv[i] = (n0 + nn < N) ? src[(size_t)(k0 + kk) * N + n0 + nn] : 0.f;
;     }
; #pragma unroll
;     for (int i = 0; i < 16; ++i) tile[tid & 63][i * 4 + (tid >> 6)] = tv[i];
; DI void phase0(const Params& p, unsigned char* smem, const int tid, const int vb, const int nvb) {
;     ...
;             if (id < 256) { transpose_tile(smem, tid, p.in[11], 1024, 1024, (bf16_t*)(ws + OFF_WDN), 1024, 0, id >> 4, id & 15); continue; }
.LBB0_79:
	s_andn2_saveexec_b64 s[4:5], s[28:29]
	s_cbranch_execz .LBB0_83
	v_lshrrev_b32_e32 v191, 4, v64
	v_and_b32_e32 v197, 15, v64
	s_mov_b64 s[88:89], 0x4000
	v_lshlrev_b32_e32 v196, 6, v191
	v_readfirstlane_b32 s91, v4
	v_add_u32_e32 v190, 0xfffffb30, v4
	v_and_b32_e32 v189, 15, v190
	v_lshrrev_b32_e32 v188, 4, v190
	v_lshlrev_b32_e32 v190, 6, v189
	v_lshlrev_b32_e32 v192, 6, v188
	v_lshl_add_u32 v198, v66, 4, v190
	v_add_u32_e32 v193, v192, v191
	v_mul_u32_u24_e32 v193, 0x400, v193
	v_add_lshl_u32 v193, v193, v198, 2
	v_sub_u32_e32 v193, v193, v196
	v_add_co_u32_e32 v194, vcc, v92, v193
	v_readfirstlane_b32 s92, v198
	v_add_lshl_u32 v199, v192, v64, 1
	v_addc_co_u32_e32 v195, vcc, 0, v93, vcc
	global_load_dword v164, v[194:195], off
	v_lshl_add_u64 v[194:195], v[194:195], 0, s[88:89]
	global_load_dword v165, v[194:195], off
	v_lshl_add_u64 v[194:195], v[194:195], 0, s[88:89]
	global_load_dword v166, v[194:195], off
	v_lshl_add_u64 v[194:195], v[194:195], 0, s[88:89]
	global_load_dword v167, v[194:195], off
	v_lshl_add_u64 v[194:195], v[194:195], 0, s[88:89]
	global_load_dword v168, v[194:195], off
	v_lshl_add_u64 v[194:195], v[194:195], 0, s[88:89]
	global_load_dword v169, v[194:195], off
	v_lshl_add_u64 v[194:195], v[194:195], 0, s[88:89]
	global_load_dword v170, v[194:195], off
	v_lshl_add_u64 v[194:195], v[194:195], 0, s[88:89]
	global_load_dword v171, v[194:195], off
	v_lshl_add_u64 v[194:195], v[194:195], 0, s[88:89]
	global_load_dword v172, v[194:195], off
	v_lshl_add_u64 v[194:195], v[194:195], 0, s[88:89]
	global_load_dword v173, v[194:195], off
	v_lshl_add_u64 v[194:195], v[194:195], 0, s[88:89]
	global_load_dword v174, v[194:195], off
	v_lshl_add_u64 v[194:195], v[194:195], 0, s[88:89]
	global_load_dword v175, v[194:195], off
	v_lshl_add_u64 v[194:195], v[194:195], 0, s[88:89]
	global_load_dword v176, v[194:195], off
	v_lshl_add_u64 v[194:195], v[194:195], 0, s[88:89]
	global_load_dword v177, v[194:195], off
	v_lshl_add_u64 v[194:195], v[194:195], 0, s[88:89]
	global_load_dword v178, v[194:195], off
	v_lshl_add_u64 v[194:195], v[194:195], 0, s[88:89]
	global_load_dword v179, v[194:195], off
	s_add_i32 s91, s91, 0x200
	s_mov_b32 s98, 0
	s_cmpk_gt_u32 s91, 0x5cf
	s_cbranch_scc1 .Lp0t_dn_l1
	v_add_u32_e32 v224, 0xfffffd30, v4
	v_and_b32_e32 v223, 15, v224
	v_lshrrev_b32_e32 v222, 4, v224
	v_lshlrev_b32_e32 v224, 6, v223
	v_lshlrev_b32_e32 v220, 6, v222
	v_lshl_add_u32 v226, v66, 4, v224
	v_add_u32_e32 v225, v220, v191
	v_mul_u32_u24_e32 v225, 0x400, v225
	v_add_lshl_u32 v225, v225, v226, 2
	v_sub_u32_e32 v225, v225, v196
	v_add_co_u32_e32 v216, vcc, v92, v225
	v_readfirstlane_b32 s100, v226
	v_add_lshl_u32 v221, v220, v64, 1
	v_addc_co_u32_e32 v217, vcc, 0, v93, vcc
	global_load_dword v200, v[216:217], off
	v_lshl_add_u64 v[216:217], v[216:217], 0, s[88:89]
	global_load_dword v201, v[216:217], off
	v_lshl_add_u64 v[216:217], v[216:217], 0, s[88:89]
	global_load_dword v202, v[216:217], off
	v_lshl_add_u64 v[216:217], v[216:217], 0, s[88:89]
	global_load_dword v203, v[216:217], off
	v_lshl_add_u64 v[216:217], v[216:217], 0, s[88:89]
	global_load_dword v204, v[216:217], off
	v_lshl_add_u64 v[216:217], v[216:217], 0, s[88:89]
	global_load_dword v205, v[216:217], off
	v_lshl_add_u64 v[216:217], v[216:217], 0, s[88:89]
	global_load_dword v206, v[216:217], off
	v_lshl_add_u64 v[216:217], v[216:217], 0, s[88:89]
	global_load_dword v207, v[216:217], off
	v_lshl_add_u64 v[216:217], v[216:217], 0, s[88:89]
	global_load_dword v208, v[216:217], off
	v_lshl_add_u64 v[216:217], v[216:217], 0, s[88:89]
	global_load_dword v209, v[216:217], off
	v_lshl_add_u64 v[216:217], v[216:217], 0, s[88:89]
	global_load_dword v210, v[216:217], off
	v_lshl_add_u64 v[216:217], v[216:217], 0, s[88:89]
	global_load_dword v211, v[216:217], off
	v_lshl_add_u64 v[216:217], v[216:217], 0, s[88:89]
	global_load_dword v212, v[216:217], off
	v_lshl_add_u64 v[216:217], v[216:217], 0, s[88:89]
	global_load_dword v213, v[216:217], off
	v_lshl_add_u64 v[216:217], v[216:217], 0, s[88:89]
	global_load_dword v214, v[216:217], off
	v_lshl_add_u64 v[216:217], v[216:217], 0, s[88:89]
	global_load_dword v215, v[216:217], off
.Lp0t_dn_l1:
	v_lshrrev_b32_e32 v186, 8, v250
	v_mul_u32_u24_e32 v195, 0x1100, v66
	v_lshlrev_b32_e32 v186, 16, v186
	v_mul_u32_u24_e32 v187, 0x110, v197
	v_add_u32_e32 v186, v186, v195
	v_lshl_add_u32 v195, v191, 2, v187
	v_add_u32_e32 v186, 0x8010, v186
	v_lshl_add_u32 v187, v64, 2, v186
	v_add_u32_e32 v195, v195, v186
	s_cmpk_gt_u32 s91, 0x5cf
	s_cbranch_scc1 .Lp0t_dn_w1
	s_waitcnt vmcnt(16)
	s_branch .Lp0t_dn_w2

; DI unsigned short f2bf(float x) { return (unsigned short)(pk2(x, 0.f) & 0xffffu); }
; DI void transpose_tile(unsigned char* smem, const int tid, const float* src, int K, int N, bf16_t* dst, int ldd, int permid, int kt, int nt) {
;     ...
;     for (int i = 0; i < 16; ++i) tile[tid & 63][i * 4 + (tid >> 6)] = tv[i];
;     __syncthreads();
; #pragma unroll 4
;     for (int i = 0; i < 16; ++i) {
;         int nn = i * 4 + (tid >> 6), kk = tid & 63;
;         int n = n0 + nn;
;         if (n < N) {
;             int row = n;
;             if (permid == 1) row = (n < 2048) ? n : ((n >= 2056) ? n - 8 : -1);
;             else if (permid == 2) row = (n < 1024) ? ((n >> 2) * 8 + (n & 3)) : (((n - 1024) >> 2) * 8 + 4 + (n & 3));
;             else if (permid == 3) row = (n < 2816) ? ((n >> 2) * 8 + (n & 3)) : (((n - 2816) >> 2) * 8 + 4 + (n & 3));
;             if (row >= 0) dst[(size_t)row * ldd + k0 + kk] = f2bf(tile[nn][kk]);
;         }
;     }
.Lp0t_dn_w2:
	ds_write2_b32 v195, v164, v165 offset0:0 offset1:4
	ds_write2_b32 v195, v166, v167 offset0:8 offset1:12
	ds_write2_b32 v195, v168, v169 offset0:16 offset1:20
	ds_write2_b32 v195, v170, v171 offset0:24 offset1:28
	ds_write2_b32 v195, v172, v173 offset0:32 offset1:36
	ds_write2_b32 v195, v174, v175 offset0:40 offset1:44
	ds_write2_b32 v195, v176, v177 offset0:48 offset1:52
	ds_write2_b32 v195, v178, v179 offset0:56 offset1:60
	s_waitcnt lgkmcnt(0)
	ds_read_b32 v164, v187 offset:0
	ds_read_b32 v165, v187 offset:272
	ds_read_b32 v166, v187 offset:544
	ds_read_b32 v167, v187 offset:816
	ds_read_b32 v168, v187 offset:1088
	ds_read_b32 v169, v187 offset:1360
	ds_read_b32 v170, v187 offset:1632
	ds_read_b32 v171, v187 offset:1904
	ds_read_b32 v172, v187 offset:2176
	ds_read_b32 v173, v187 offset:2448
	ds_read_b32 v174, v187 offset:2720
	ds_read_b32 v175, v187 offset:2992
	ds_read_b32 v176, v187 offset:3264
	ds_read_b32 v177, v187 offset:3536
	ds_read_b32 v178, v187 offset:3808
	ds_read_b32 v179, v187 offset:4080
	s_add_i32 s93, s92, 0
	s_mov_b32 s94, s93
	s_mul_i32 s94, s94, 0x800
	s_add_i32 s94, s94, 0x980000
	s_waitcnt lgkmcnt(15)
	v_cvt_pk_bf16_f32 v180, v164, v164
	v_add_u32_e32 v228, s94, v199
	global_store_short v228, v180, s[70:71]
	s_add_i32 s93, s92, 1
	s_mov_b32 s94, s93
	s_mul_i32 s94, s94, 0x800
	s_add_i32 s94, s94, 0x980000
	s_waitcnt lgkmcnt(14)
	v_cvt_pk_bf16_f32 v181, v165, v165
	v_add_u32_e32 v229, s94, v199
	global_store_short v229, v181, s[70:71]
	s_add_i32 s93, s92, 2
	s_mov_b32 s94, s93
	s_mul_i32 s94, s94, 0x800
	s_add_i32 s94, s94, 0x980000
	s_waitcnt lgkmcnt(13)
	v_cvt_pk_bf16_f32 v182, v166, v166
	v_add_u32_e32 v230, s94, v199
	global_store_short v230, v182, s[70:71]
	s_add_i32 s93, s92, 3
	s_mov_b32 s94, s93
	s_mul_i32 s94, s94, 0x800
	s_add_i32 s94, s94, 0x980000
	s_waitcnt lgkmcnt(12)
	v_cvt_pk_bf16_f32 v183, v167, v167
	v_add_u32_e32 v231, s94, v199
	global_store_short v231, v183, s[70:71]
	s_add_i32 s93, s92, 4
	s_mov_b32 s94, s93
	s_mul_i32 s94, s94, 0x800
	s_add_i32 s94, s94, 0x980000
	s_waitcnt lgkmcnt(11)
	v_cvt_pk_bf16_f32 v184, v168, v168
	v_add_u32_e32 v228, s94, v199
	global_store_short v228, v184, s[70:71]
	s_add_i32 s93, s92, 5
	s_mov_b32 s94, s93
	s_mul_i32 s94, s94, 0x800
	s_add_i32 s94, s94, 0x980000
	s_waitcnt lgkmcnt(10)
	v_cvt_pk_bf16_f32 v185, v169, v169
	v_add_u32_e32 v229, s94, v199
	global_store_short v229, v185, s[70:71]
	s_add_i32 s93, s92, 6
	s_mov_b32 s94, s93
	s_mul_i32 s94, s94, 0x800
	s_add_i32 s94, s94, 0x980000
	s_waitcnt lgkmcnt(9)
	v_cvt_pk_bf16_f32 v180, v170, v170
	v_add_u32_e32 v230, s94, v199
	global_store_short v230, v180, s[70:71]
	s_add_i32 s93, s92, 7
	s_mov_b32 s94, s93
	s_mul_i32 s94, s94, 0x800
	s_add_i32 s94, s94, 0x980000
	s_waitcnt lgkmcnt(8)
	v_cvt_pk_bf16_f32 v181, v171, v171
	v_add_u32_e32 v231, s94, v199
	global_store_short v231, v181, s[70:71]
	s_add_i32 s93, s92, 8
	s_mov_b32 s94, s93
	s_mul_i32 s94, s94, 0x800
	s_add_i32 s94, s94, 0x980000
	s_waitcnt lgkmcnt(7)
	v_cvt_pk_bf16_f32 v182, v172, v172
	v_add_u32_e32 v228, s94, v199
	global_store_short v228, v182, s[70:71]
	s_add_i32 s93, s92, 9
	s_mov_b32 s94, s93
	s_mul_i32 s94, s94, 0x800
	s_add_i32 s94, s94, 0x980000
	s_waitcnt lgkmcnt(6)
	v_cvt_pk_bf16_f32 v183, v173, v173
	v_add_u32_e32 v229, s94, v199
	global_store_short v229, v183, s[70:71]
	s_add_i32 s93, s92, 10
	s_mov_b32 s94, s93
	s_mul_i32 s94, s94, 0x800
	s_add_i32 s94, s94, 0x980000
	s_waitcnt lgkmcnt(5)
	v_cvt_pk_bf16_f32 v184, v174, v174
	v_add_u32_e32 v230, s94, v199
	global_store_short v230, v184, s[70:71]
	s_add_i32 s93, s92, 11
	s_mov_b32 s94, s93
	s_mul_i32 s94, s94, 0x800
	s_add_i32 s94, s94, 0x980000
	s_waitcnt lgkmcnt(4)
	v_cvt_pk_bf16_f32 v185, v175, v175
	v_add_u32_e32 v231, s94, v199
	global_store_short v231, v185, s[70:71]
	s_add_i32 s93, s92, 12
	s_mov_b32 s94, s93
	s_mul_i32 s94, s94, 0x800
	s_add_i32 s94, s94, 0x980000
	s_waitcnt lgkmcnt(3)
	v_cvt_pk_bf16_f32 v180, v176, v176
	v_add_u32_e32 v228, s94, v199
	global_store_short v228, v180, s[70:71]
	s_add_i32 s93, s92, 13
	s_mov_b32 s94, s93
	s_mul_i32 s94, s94, 0x800
	s_add_i32 s94, s94, 0x980000
	s_waitcnt lgkmcnt(2)
	v_cvt_pk_bf16_f32 v181, v177, v177
	v_add_u32_e32 v229, s94, v199
	global_store_short v229, v181, s[70:71]
	s_add_i32 s93, s92, 14
	s_mov_b32 s94, s93
	s_mul_i32 s94, s94, 0x800
	s_add_i32 s94, s94, 0x980000
	s_waitcnt lgkmcnt(1)
	v_cvt_pk_bf16_f32 v182, v178, v178
	v_add_u32_e32 v230, s94, v199
	global_store_short v230, v182, s[70:71]
	s_add_i32 s93, s92, 15
	s_mov_b32 s94, s93
	s_mul_i32 s94, s94, 0x800
	s_add_i32 s94, s94, 0x980000
	s_waitcnt lgkmcnt(0)
	v_cvt_pk_bf16_f32 v183, v179, v179
	v_add_u32_e32 v231, s94, v199
	global_store_short v231, v183, s[70:71]
	s_cmpk_gt_u32 s91, 0x5cf
	s_cbranch_scc1 .Lp0t_dn_done
; DI unsigned short f2bf(float x) { return (unsigned short)(pk2(x, 0.f) & 0xffffu); }
; DI void transpose_tile(unsigned char* smem, const int tid, const float* src, int K, int N, bf16_t* dst, int ldd, int permid, int kt, int nt) {
;     ...
;     for (int i = 0; i < 16; ++i) tile[tid & 63][i * 4 + (tid >> 6)] = tv[i];
;     __syncthreads();
; #pragma unroll 4
;     for (int i = 0; i < 16; ++i) {
;         int nn = i * 4 + (tid >> 6), kk = tid & 63;
;         int n = n0 + nn;
;         if (n < N) {
;             int row = n;
;             if (permid == 1) row = (n < 2048) ? n : ((n >= 2056) ? n - 8 : -1);
;             else if (permid == 2) row = (n < 1024) ? ((n >> 2) * 8 + (n & 3)) : (((n - 1024) >> 2) * 8 + 4 + (n & 3));
;             else if (permid == 3) row = (n < 2816) ? ((n >> 2) * 8 + (n & 3)) : (((n - 2816) >> 2) * 8 + 4 + (n & 3));
;             if (row >= 0) dst[(size_t)row * ldd + k0 + kk] = f2bf(tile[nn][kk]);
;         }
;     }
	s_waitcnt vmcnt(16)
	ds_write2_b32 v195, v200, v201 offset0:0 offset1:4
	ds_write2_b32 v195, v202, v203 offset0:8 offset1:12
	ds_write2_b32 v195, v204, v205 offset0:16 offset1:20
	ds_write2_b32 v195, v206, v207 offset0:24 offset1:28
	ds_write2_b32 v195, v208, v209 offset0:32 offset1:36
	ds_write2_b32 v195, v210, v211 offset0:40 offset1:44
	ds_write2_b32 v195, v212, v213 offset0:48 offset1:52
	ds_write2_b32 v195, v214, v215 offset0:56 offset1:60
	s_waitcnt lgkmcnt(0)
	ds_read_b32 v200, v187 offset:0
	ds_read_b32 v201, v187 offset:272
	ds_read_b32 v202, v187 offset:544
	ds_read_b32 v203, v187 offset:816
	ds_read_b32 v204, v187 offset:1088
	ds_read_b32 v205, v187 offset:1360
	ds_read_b32 v206, v187 offset:1632
	ds_read_b32 v207, v187 offset:1904
	ds_read_b32 v208, v187 offset:2176
	ds_read_b32 v209, v187 offset:2448
	ds_read_b32 v210, v187 offset:2720
	ds_read_b32 v211, v187 offset:2992
	ds_read_b32 v212, v187 offset:3264
	ds_read_b32 v213, v187 offset:3536
	ds_read_b32 v214, v187 offset:3808
	ds_read_b32 v215, v187 offset:4080
	s_add_i32 s93, s100, 0
	s_mov_b32 s94, s93
	s_mul_i32 s94, s94, 0x800
	s_add_i32 s94, s94, 0x980000
	s_waitcnt lgkmcnt(15)
	v_cvt_pk_bf16_f32 v180, v200, v200
	v_add_u32_e32 v228, s94, v221
	global_store_short v228, v180, s[70:71]
	s_add_i32 s93, s100, 1
	s_mov_b32 s94, s93
	s_mul_i32 s94, s94, 0x800
	s_add_i32 s94, s94, 0x980000
	s_waitcnt lgkmcnt(14)
	v_cvt_pk_bf16_f32 v181, v201, v201
	v_add_u32_e32 v229, s94, v221
	global_store_short v229, v181, s[70:71]
	s_add_i32 s93, s100, 2
	s_mov_b32 s94, s93
	s_mul_i32 s94, s94, 0x800
	s_add_i32 s94, s94, 0x980000
	s_waitcnt lgkmcnt(13)
	v_cvt_pk_bf16_f32 v182, v202, v202
	v_add_u32_e32 v230, s94, v221
	global_store_short v230, v182, s[70:71]
	s_add_i32 s93, s100, 3
	s_mov_b32 s94, s93
	s_mul_i32 s94, s94, 0x800
	s_add_i32 s94, s94, 0x980000
	s_waitcnt lgkmcnt(12)
	v_cvt_pk_bf16_f32 v183, v203, v203
	v_add_u32_e32 v231, s94, v221
	global_store_short v231, v183, s[70:71]
	s_add_i32 s93, s100, 4
	s_mov_b32 s94, s93
	s_mul_i32 s94, s94, 0x800
	s_add_i32 s94, s94, 0x980000
	s_waitcnt lgkmcnt(11)
	v_cvt_pk_bf16_f32 v184, v204, v204
	v_add_u32_e32 v228, s94, v221
	global_store_short v228, v184, s[70:71]
	s_add_i32 s93, s100, 5
	s_mov_b32 s94, s93
	s_mul_i32 s94, s94, 0x800
	s_add_i32 s94, s94, 0x980000
	s_waitcnt lgkmcnt(10)
	v_cvt_pk_bf16_f32 v185, v205, v205
	v_add_u32_e32 v229, s94, v221
	global_store_short v229, v185, s[70:71]
	s_add_i32 s93, s100, 6
	s_mov_b32 s94, s93
	s_mul_i32 s94, s94, 0x800
	s_add_i32 s94, s94, 0x980000
	s_waitcnt lgkmcnt(9)
	v_cvt_pk_bf16_f32 v180, v206, v206
	v_add_u32_e32 v230, s94, v221
	global_store_short v230, v180, s[70:71]
	s_add_i32 s93, s100, 7
	s_mov_b32 s94, s93
	s_mul_i32 s94, s94, 0x800
	s_add_i32 s94, s94, 0x980000
	s_waitcnt lgkmcnt(8)
	v_cvt_pk_bf16_f32 v181, v207, v207
	v_add_u32_e32 v231, s94, v221
	global_store_short v231, v181, s[70:71]
	s_add_i32 s93, s100, 8
	s_mov_b32 s94, s93
	s_mul_i32 s94, s94, 0x800
	s_add_i32 s94, s94, 0x980000
	s_waitcnt lgkmcnt(7)
	v_cvt_pk_bf16_f32 v182, v208, v208
	v_add_u32_e32 v228, s94, v221
	global_store_short v228, v182, s[70:71]
	s_add_i32 s93, s100, 9
	s_mov_b32 s94, s93
	s_mul_i32 s94, s94, 0x800
	s_add_i32 s94, s94, 0x980000
	s_waitcnt lgkmcnt(6)
	v_cvt_pk_bf16_f32 v183, v209, v209
	v_add_u32_e32 v229, s94, v221
	global_store_short v229, v183, s[70:71]
	s_add_i32 s93, s100, 10
	s_mov_b32 s94, s93
	s_mul_i32 s94, s94, 0x800
	s_add_i32 s94, s94, 0x980000
	s_waitcnt lgkmcnt(5)
	v_cvt_pk_bf16_f32 v184, v210, v210
	v_add_u32_e32 v230, s94, v221
	global_store_short v230, v184, s[70:71]
	s_add_i32 s93, s100, 11
	s_mov_b32 s94, s93
	s_mul_i32 s94, s94, 0x800
	s_add_i32 s94, s94, 0x980000
	s_waitcnt lgkmcnt(4)
	v_cvt_pk_bf16_f32 v185, v211, v211
	v_add_u32_e32 v231, s94, v221
	global_store_short v231, v185, s[70:71]
	s_add_i32 s93, s100, 12
	s_mov_b32 s94, s93
	s_mul_i32 s94, s94, 0x800
	s_add_i32 s94, s94, 0x980000
	s_waitcnt lgkmcnt(3)
	v_cvt_pk_bf16_f32 v180, v212, v212
	v_add_u32_e32 v228, s94, v221
	global_store_short v228, v180, s[70:71]
	s_add_i32 s93, s100, 13
	s_mov_b32 s94, s93
	s_mul_i32 s94, s94, 0x800
	s_add_i32 s94, s94, 0x980000
	s_waitcnt lgkmcnt(2)
	v_cvt_pk_bf16_f32 v181, v213, v213
	v_add_u32_e32 v229, s94, v221
	global_store_short v229, v181, s[70:71]
	s_add_i32 s93, s100, 14
	s_mov_b32 s94, s93
	s_mul_i32 s94, s94, 0x800
	s_add_i32 s94, s94, 0x980000
	s_waitcnt lgkmcnt(1)
	v_cvt_pk_bf16_f32 v182, v214, v214
	v_add_u32_e32 v230, s94, v221
	global_store_short v230, v182, s[70:71]
	s_add_i32 s93, s100, 15
	s_mov_b32 s94, s93
	s_mul_i32 s94, s94, 0x800
	s_add_i32 s94, s94, 0x980000
	s_waitcnt lgkmcnt(0)
	v_cvt_pk_bf16_f32 v183, v215, v215
	v_add_u32_e32 v231, s94, v221
	global_store_short v231, v183, s[70:71]
	v_add_u32_e32 v67, s90, v67
	v_add_u16_e32 v117, s90, v117
